# out-projection fast epilogue also for layer 0 (residual from the f32 input rows, loads run six quads ahead through a register ring)
# speedup vs baseline: 1.0084x; 1.0002x over previous
.LBB0_560:
	s_branch .Lfo_entry
	s_lshr_b32 s14, s34, 3
	s_mulk_i32 s14, 0xc00
	s_ashr_i32 s15, s14, 31
	s_lshl_b64 s[14:15], s[14:15], 2
	s_add_u32 s16, s86, s14
	s_addc_u32 s17, s87, s15
	s_add_u32 s16, s16, 0x2000
	s_addc_u32 s17, s17, 0
	s_waitcnt lgkmcnt(0)
	v_lshl_add_u64 v[0:1], v[170:171], 2, s[16:17]
	global_load_dwordx4 v[142:145], v[0:1], off
	s_add_u32 s14, s88, s14
	s_addc_u32 s15, s89, s15
	s_add_u32 s86, s14, 0x1000
	v_mov_b32_e32 v186, 0
	v_cndmask_b32_e64 v0, 0, 1, s[40:41]
	s_addc_u32 s87, s15, 0
	v_cmp_ne_u32_e64 s[14:15], 1, v0
	s_andn2_b64 vcc, exec, s[40:41]
	v_mov_b32_e32 v190, 0
	v_mov_b32_e32 v191, v186
	v_mov_b32_e32 v192, 0
	v_mov_b32_e32 v193, 0
	s_cbranch_vccnz .LBB0_562
	v_lshlrev_b64 v[4:5], 2, v[170:171]
	v_lshl_add_u64 v[0:1], s[86:87], 0, v[4:5]
	global_load_dwordx4 v[0:3], v[0:1], off
	v_lshl_add_u64 v[4:5], s[26:27], 0, v[4:5]
	global_load_dwordx4 v[4:7], v[4:5], off
	s_waitcnt vmcnt(0)
	v_pk_add_f32 v[2:3], v[2:3], 1.0 op_sel_hi:[1,0]
	v_pk_add_f32 v[0:1], v[0:1], 1.0 op_sel_hi:[1,0]
	v_pk_mul_f32 v[192:193], v[6:7], v[2:3]
	v_pk_mul_f32 v[190:191], v[4:5], v[0:1]

.Lfo_entry:
	s_and_b64 vcc, exec, s[28:29]
	s_cbranch_vccz .Lfo_first
	s_lshr_b32 s14, s34, 3
	s_mul_i32 s14, s14, 0x3000
	s_add_u32 s16, s86, s14
	s_addc_u32 s17, s87, 0
	s_add_u32 s16, s16, 0x2000
	s_addc_u32 s17, s17, 0
	s_add_u32 s86, s88, s14
	s_addc_u32 s87, s89, 0
	s_add_u32 s86, s86, 0x1000
	s_addc_u32 s87, s87, 0
	v_lshl_add_u32 v171, v170, 1, v96
	v_lshl_add_u32 v171, v222, 11, v171
	v_lshlrev_b32_e32 v170, 2, v170
	s_lshl_b32 s14, s34, 8
	s_add_i32 s14, s14, s81
	s_lshl_b32 s12, s14, 11
	s_add_u32 s14, s2, s12
	s_addc_u32 s15, s3, 0
	s_add_u32 s78, s78, s12
	s_addc_u32 s79, s79, 0
	s_add_u32 s22, s78, 0x4000
	s_addc_u32 s23, s79, 0
	s_mov_b64 s[2:3], s[14:15]
	s_add_u32 s18, s14, 0x4000
	s_addc_u32 s19, s15, 0
	s_mov_b64 s[12:13], s[18:19]
	s_and_b64 vcc, exec, s[40:41]
	s_cbranch_vccz .Lfo_nong
	global_load_dwordx4 v[142:145], v170, s[16:17]
	global_load_dwordx4 v[150:153], v170, s[16:17] offset:16
	global_load_dwordx4 v[138:141], v170, s[16:17] offset:128
	global_load_dwordx4 v[146:149], v170, s[16:17] offset:144
	global_load_dwordx4 v[196:199], v171, s[14:15]
	global_load_dwordx4 v[200:203], v171, s[12:13]
	s_add_u32 s14, s14, 0x8000
	s_addc_u32 s15, s15, 0
	s_add_u32 s12, s12, 0x8000
	s_addc_u32 s13, s13, 0
	global_load_dwordx4 v[204:207], v171, s[14:15]
	global_load_dwordx4 v[234:237], v171, s[12:13]
	global_load_dwordx4 v[180:183], v170, s[86:87]
	global_load_dwordx4 v[184:187], v170, s[86:87] offset:16
	global_load_dwordx4 v[188:191], v170, s[86:87] offset:128
	global_load_dwordx4 v[192:195], v170, s[86:87] offset:144
	global_load_dwordx4 v[0:3], v170, s[26:27]
	global_load_dwordx4 v[4:7], v170, s[26:27] offset:16
	global_load_dwordx4 v[238:241], v170, s[26:27] offset:128
	global_load_dwordx4 v[242:245], v170, s[26:27] offset:144
	s_waitcnt vmcnt(0)
	v_pk_add_f32 v[182:183], v[182:183], 1.0 op_sel_hi:[1,0]
	v_pk_add_f32 v[180:181], v[180:181], 1.0 op_sel_hi:[1,0]
	v_pk_add_f32 v[186:187], v[186:187], 1.0 op_sel_hi:[1,0]
	v_pk_add_f32 v[184:185], v[184:185], 1.0 op_sel_hi:[1,0]
	v_pk_add_f32 v[190:191], v[190:191], 1.0 op_sel_hi:[1,0]
	v_pk_add_f32 v[188:189], v[188:189], 1.0 op_sel_hi:[1,0]
	v_pk_add_f32 v[194:195], v[194:195], 1.0 op_sel_hi:[1,0]
	v_pk_add_f32 v[192:193], v[192:193], 1.0 op_sel_hi:[1,0]
	v_pk_mul_f32 v[182:183], v[2:3], v[182:183]
	v_pk_mul_f32 v[180:181], v[0:1], v[180:181]
	v_pk_mul_f32 v[186:187], v[6:7], v[186:187]
	v_pk_mul_f32 v[184:185], v[4:5], v[184:185]
	v_pk_mul_f32 v[190:191], v[240:241], v[190:191]
	v_pk_mul_f32 v[188:189], v[238:239], v[188:189]
	v_pk_mul_f32 v[194:195], v[244:245], v[194:195]
	v_pk_mul_f32 v[192:193], v[242:243], v[192:193]
	s_add_u32 s14, s14, 0x8000
	s_addc_u32 s15, s15, 0
	s_add_u32 s12, s12, 0x8000
	s_addc_u32 s13, s13, 0
	global_load_dwordx4 v[238:241], v171, s[14:15]
	global_load_dwordx4 v[242:245], v171, s[12:13]
	s_waitcnt vmcnt(2)
	s_mov_b64 vcc, s[6:7]
	v_cndmask_b32_dpp v0, v200, v196, vcc row_ror:8 row_mask:0xf bank_mask:0xf
	v_cndmask_b32_dpp v1, v201, v197, vcc row_ror:8 row_mask:0xf bank_mask:0xf
	v_cndmask_b32_dpp v2, v202, v198, vcc row_ror:8 row_mask:0xf bank_mask:0xf
	v_cndmask_b32_dpp v3, v203, v199, vcc row_ror:8 row_mask:0xf bank_mask:0xf
	s_not_b64 vcc, s[6:7]
	v_cndmask_b32_dpp v4, v196, v200, vcc row_ror:8 row_mask:0xf bank_mask:0xf
	v_cndmask_b32_dpp v5, v197, v201, vcc row_ror:8 row_mask:0xf bank_mask:0xf
	v_cndmask_b32_dpp v6, v198, v202, vcc row_ror:8 row_mask:0xf bank_mask:0xf
	v_cndmask_b32_dpp v7, v199, v203, vcc row_ror:8 row_mask:0xf bank_mask:0xf
	s_add_u32 s14, s14, 0x8000
	s_addc_u32 s15, s15, 0
	s_add_u32 s12, s12, 0x8000
	s_addc_u32 s13, s13, 0
	global_load_dwordx4 v[196:199], v171, s[14:15]
	global_load_dwordx4 v[200:203], v171, s[12:13]
	v_lshlrev_b32_e32 v246, 16, v0
	v_and_b32_e32 v247, 0xffff0000, v0
	v_pk_fma_f32 v[134:135], v[134:135], v[142:143], v[246:247]
	v_lshlrev_b32_e32 v248, 16, v1
	v_and_b32_e32 v249, 0xffff0000, v1
	v_pk_fma_f32 v[136:137], v[136:137], v[144:145], v[248:249]
	v_lshlrev_b32_e32 v250, 16, v2
	v_and_b32_e32 v251, 0xffff0000, v2
	v_pk_fma_f32 v[130:131], v[130:131], v[150:151], v[250:251]
	v_lshlrev_b32_e32 v208, 16, v3
	v_and_b32_e32 v209, 0xffff0000, v3
	v_pk_fma_f32 v[132:133], v[132:133], v[152:153], v[208:209]
	v_lshlrev_b32_e32 v246, 16, v4
	v_and_b32_e32 v247, 0xffff0000, v4
	v_pk_fma_f32 v[126:127], v[126:127], v[138:139], v[246:247]
	v_lshlrev_b32_e32 v248, 16, v5
	v_and_b32_e32 v249, 0xffff0000, v5
	v_pk_fma_f32 v[128:129], v[128:129], v[140:141], v[248:249]
	v_lshlrev_b32_e32 v250, 16, v6
	v_and_b32_e32 v251, 0xffff0000, v6
	v_pk_fma_f32 v[122:123], v[122:123], v[146:147], v[250:251]
	v_lshlrev_b32_e32 v208, 16, v7
	v_and_b32_e32 v209, 0xffff0000, v7
	v_pk_fma_f32 v[124:125], v[124:125], v[148:149], v[208:209]
	v_cvt_pk_bf16_f32 v0, v134, v135
	v_cvt_pk_bf16_f32 v1, v136, v137
	v_cvt_pk_bf16_f32 v2, v130, v131
	v_cvt_pk_bf16_f32 v3, v132, v133
	v_cvt_pk_bf16_f32 v4, v126, v127
	v_cvt_pk_bf16_f32 v5, v128, v129
	v_cvt_pk_bf16_f32 v6, v122, v123
	v_cvt_pk_bf16_f32 v7, v124, v125
	v_mul_f32_e32 v246, v135, v135
	v_mul_f32_e32 v248, v137, v137
	v_fmac_f32_e32 v246, v134, v134
	v_fmac_f32_e32 v248, v136, v136
	v_add_f32_e32 v246, v246, v248
	v_mul_f32_e32 v248, v131, v131
	v_fmac_f32_e32 v248, v130, v130
	v_add_f32_e32 v246, v246, v248
	v_mul_f32_e32 v248, v133, v133
	v_fmac_f32_e32 v248, v132, v132
	v_add_f32_e32 v246, v248, v246
	v_mul_f32_e32 v247, v127, v127
	v_mul_f32_e32 v248, v129, v129
	v_fmac_f32_e32 v247, v126, v126
	v_fmac_f32_e32 v248, v128, v128
	v_add_f32_e32 v247, v247, v248
	v_mul_f32_e32 v248, v123, v123
	v_fmac_f32_e32 v248, v122, v122
	v_add_f32_e32 v247, v247, v248
	v_mul_f32_e32 v248, v125, v125
	v_fmac_f32_e32 v248, v124, v124
	v_add_f32_e32 v247, v248, v247
	v_add_f32_e32 v246, v246, v247
	v_mov_b32_e32 v247, v246
	s_nop 1
	v_permlane16_swap_b32_e32 v246, v247
	s_nop 1
	v_add_f32_e32 v246, v246, v247
	v_mov_b32_e32 v247, v246
	s_nop 1
	v_permlane32_swap_b32_e32 v246, v247
	v_add_u32_e32 v248, s8, v223
	s_nop 0
	v_add_f32_e32 v246, v246, v247
	s_mov_b64 exec, s[44:45]
	ds_write_b32 v248, v246
	s_mov_b64 exec, -1
	v_pk_mul_f32 v[134:135], v[180:181], v[134:135]
	v_pk_mul_f32 v[136:137], v[182:183], v[136:137]
	v_pk_mul_f32 v[130:131], v[184:185], v[130:131]
	v_pk_mul_f32 v[132:133], v[186:187], v[132:133]
	v_pk_mul_f32 v[126:127], v[188:189], v[126:127]
	v_pk_mul_f32 v[128:129], v[190:191], v[128:129]
	v_pk_mul_f32 v[122:123], v[192:193], v[122:123]
	v_pk_mul_f32 v[124:125], v[194:195], v[124:125]
	v_cvt_pk_bf16_f32 v246, v134, v135
	v_cvt_pk_bf16_f32 v247, v136, v137
	v_cvt_pk_bf16_f32 v248, v130, v131
	v_cvt_pk_bf16_f32 v249, v132, v133
	v_cvt_pk_bf16_f32 v250, v126, v127
	v_cvt_pk_bf16_f32 v251, v128, v129
	v_cvt_pk_bf16_f32 v208, v122, v123
	v_cvt_pk_bf16_f32 v209, v124, v125
	s_nop 1
	s_mov_b64 vcc, s[6:7]
	v_cndmask_b32_dpp v134, v4, v0, vcc row_ror:8 row_mask:0xf bank_mask:0xf
	v_cndmask_b32_dpp v135, v5, v1, vcc row_ror:8 row_mask:0xf bank_mask:0xf
	v_cndmask_b32_dpp v136, v6, v2, vcc row_ror:8 row_mask:0xf bank_mask:0xf
	v_cndmask_b32_dpp v137, v7, v3, vcc row_ror:8 row_mask:0xf bank_mask:0xf
	v_cndmask_b32_dpp v126, v250, v246, vcc row_ror:8 row_mask:0xf bank_mask:0xf
	v_cndmask_b32_dpp v127, v251, v247, vcc row_ror:8 row_mask:0xf bank_mask:0xf
	v_cndmask_b32_dpp v128, v208, v248, vcc row_ror:8 row_mask:0xf bank_mask:0xf
	v_cndmask_b32_dpp v129, v209, v249, vcc row_ror:8 row_mask:0xf bank_mask:0xf
	s_not_b64 vcc, s[6:7]
	v_cndmask_b32_dpp v130, v0, v4, vcc row_ror:8 row_mask:0xf bank_mask:0xf
	v_cndmask_b32_dpp v131, v1, v5, vcc row_ror:8 row_mask:0xf bank_mask:0xf
	v_cndmask_b32_dpp v132, v2, v6, vcc row_ror:8 row_mask:0xf bank_mask:0xf
	v_cndmask_b32_dpp v133, v3, v7, vcc row_ror:8 row_mask:0xf bank_mask:0xf
	v_cndmask_b32_dpp v122, v246, v250, vcc row_ror:8 row_mask:0xf bank_mask:0xf
	v_cndmask_b32_dpp v123, v247, v251, vcc row_ror:8 row_mask:0xf bank_mask:0xf
	v_cndmask_b32_dpp v124, v248, v208, vcc row_ror:8 row_mask:0xf bank_mask:0xf
	v_cndmask_b32_dpp v125, v249, v209, vcc row_ror:8 row_mask:0xf bank_mask:0xf
	global_store_dwordx4 v171, v[134:137], s[2:3]
	global_store_dwordx4 v171, v[130:133], s[18:19]
	global_store_dwordx4 v171, v[126:129], s[78:79]
	global_store_dwordx4 v171, v[122:125], s[22:23]
	s_waitcnt vmcnt(8)
	s_mov_b64 vcc, s[6:7]
	v_cndmask_b32_dpp v0, v234, v204, vcc row_ror:8 row_mask:0xf bank_mask:0xf
	v_cndmask_b32_dpp v1, v235, v205, vcc row_ror:8 row_mask:0xf bank_mask:0xf
	v_cndmask_b32_dpp v2, v236, v206, vcc row_ror:8 row_mask:0xf bank_mask:0xf
	v_cndmask_b32_dpp v3, v237, v207, vcc row_ror:8 row_mask:0xf bank_mask:0xf
	s_not_b64 vcc, s[6:7]
	v_cndmask_b32_dpp v4, v204, v234, vcc row_ror:8 row_mask:0xf bank_mask:0xf
	v_cndmask_b32_dpp v5, v205, v235, vcc row_ror:8 row_mask:0xf bank_mask:0xf
	v_cndmask_b32_dpp v6, v206, v236, vcc row_ror:8 row_mask:0xf bank_mask:0xf
	v_cndmask_b32_dpp v7, v207, v237, vcc row_ror:8 row_mask:0xf bank_mask:0xf
	s_add_u32 s14, s14, 0x28000
	s_addc_u32 s15, s15, 0
	s_add_u32 s12, s12, 0x28000
	s_addc_u32 s13, s13, 0
	global_load_dwordx4 v[204:207], v171, s[14:15]
	global_load_dwordx4 v[234:237], v171, s[12:13]
	v_lshlrev_b32_e32 v246, 16, v0
	v_and_b32_e32 v247, 0xffff0000, v0
	v_pk_fma_f32 v[118:119], v[118:119], v[142:143], v[246:247]
	v_lshlrev_b32_e32 v248, 16, v1
	v_and_b32_e32 v249, 0xffff0000, v1
	v_pk_fma_f32 v[120:121], v[120:121], v[144:145], v[248:249]
	v_lshlrev_b32_e32 v250, 16, v2
	v_and_b32_e32 v251, 0xffff0000, v2
	v_pk_fma_f32 v[114:115], v[114:115], v[150:151], v[250:251]
	v_lshlrev_b32_e32 v208, 16, v3
	v_and_b32_e32 v209, 0xffff0000, v3
	v_pk_fma_f32 v[116:117], v[116:117], v[152:153], v[208:209]
	v_lshlrev_b32_e32 v246, 16, v4
	v_and_b32_e32 v247, 0xffff0000, v4
	v_pk_fma_f32 v[110:111], v[110:111], v[138:139], v[246:247]
	v_lshlrev_b32_e32 v248, 16, v5
	v_and_b32_e32 v249, 0xffff0000, v5
	v_pk_fma_f32 v[112:113], v[112:113], v[140:141], v[248:249]
	v_lshlrev_b32_e32 v250, 16, v6
	v_and_b32_e32 v251, 0xffff0000, v6
	v_pk_fma_f32 v[106:107], v[106:107], v[146:147], v[250:251]
	v_lshlrev_b32_e32 v208, 16, v7
	v_and_b32_e32 v209, 0xffff0000, v7
	v_pk_fma_f32 v[108:109], v[108:109], v[148:149], v[208:209]
	v_cvt_pk_bf16_f32 v0, v118, v119
	v_cvt_pk_bf16_f32 v1, v120, v121
	v_cvt_pk_bf16_f32 v2, v114, v115
	v_cvt_pk_bf16_f32 v3, v116, v117
	v_cvt_pk_bf16_f32 v4, v110, v111
	v_cvt_pk_bf16_f32 v5, v112, v113
	v_cvt_pk_bf16_f32 v6, v106, v107
	v_cvt_pk_bf16_f32 v7, v108, v109
	v_mul_f32_e32 v246, v119, v119
	v_mul_f32_e32 v248, v121, v121
	v_fmac_f32_e32 v246, v118, v118
	v_fmac_f32_e32 v248, v120, v120
	v_add_f32_e32 v246, v246, v248
	v_mul_f32_e32 v248, v115, v115
	v_fmac_f32_e32 v248, v114, v114
	v_add_f32_e32 v246, v246, v248
	v_mul_f32_e32 v248, v117, v117
	v_fmac_f32_e32 v248, v116, v116
	v_add_f32_e32 v246, v248, v246
	v_mul_f32_e32 v247, v111, v111
	v_mul_f32_e32 v248, v113, v113
	v_fmac_f32_e32 v247, v110, v110
	v_fmac_f32_e32 v248, v112, v112
	v_add_f32_e32 v247, v247, v248
	v_mul_f32_e32 v248, v107, v107
	v_fmac_f32_e32 v248, v106, v106
	v_add_f32_e32 v247, v247, v248
	v_mul_f32_e32 v248, v109, v109
	v_fmac_f32_e32 v248, v108, v108
	v_add_f32_e32 v247, v248, v247
	v_add_f32_e32 v246, v246, v247
	v_mov_b32_e32 v247, v246
	s_nop 1
	v_permlane16_swap_b32_e32 v246, v247
	s_nop 1
	v_add_f32_e32 v246, v246, v247
	v_mov_b32_e32 v247, v246
	s_nop 1
	v_permlane32_swap_b32_e32 v246, v247
	v_add_u32_e32 v248, s8, v223
	s_nop 0
	v_add_f32_e32 v246, v246, v247
	s_mov_b64 exec, s[44:45]
	ds_write_b32 v248, v246 offset:256
	s_mov_b64 exec, -1
	v_pk_mul_f32 v[118:119], v[180:181], v[118:119]
	v_pk_mul_f32 v[120:121], v[182:183], v[120:121]
	v_pk_mul_f32 v[114:115], v[184:185], v[114:115]
	v_pk_mul_f32 v[116:117], v[186:187], v[116:117]
	v_pk_mul_f32 v[110:111], v[188:189], v[110:111]
	v_pk_mul_f32 v[112:113], v[190:191], v[112:113]
	v_pk_mul_f32 v[106:107], v[192:193], v[106:107]
	v_pk_mul_f32 v[108:109], v[194:195], v[108:109]
	v_cvt_pk_bf16_f32 v246, v118, v119
	v_cvt_pk_bf16_f32 v247, v120, v121
	v_cvt_pk_bf16_f32 v248, v114, v115
	v_cvt_pk_bf16_f32 v249, v116, v117
	v_cvt_pk_bf16_f32 v250, v110, v111
	v_cvt_pk_bf16_f32 v251, v112, v113
	v_cvt_pk_bf16_f32 v208, v106, v107
	v_cvt_pk_bf16_f32 v209, v108, v109
	s_add_u32 s2, s2, 0x8000
	s_addc_u32 s3, s3, 0
	s_add_u32 s18, s18, 0x8000
	s_addc_u32 s19, s19, 0
	s_add_u32 s78, s78, 0x8000
	s_addc_u32 s79, s79, 0
	s_add_u32 s22, s22, 0x8000
	s_addc_u32 s23, s23, 0
	s_mov_b64 vcc, s[6:7]
	v_cndmask_b32_dpp v118, v4, v0, vcc row_ror:8 row_mask:0xf bank_mask:0xf
	v_cndmask_b32_dpp v119, v5, v1, vcc row_ror:8 row_mask:0xf bank_mask:0xf
	v_cndmask_b32_dpp v120, v6, v2, vcc row_ror:8 row_mask:0xf bank_mask:0xf
	v_cndmask_b32_dpp v121, v7, v3, vcc row_ror:8 row_mask:0xf bank_mask:0xf
	v_cndmask_b32_dpp v110, v250, v246, vcc row_ror:8 row_mask:0xf bank_mask:0xf
	v_cndmask_b32_dpp v111, v251, v247, vcc row_ror:8 row_mask:0xf bank_mask:0xf
	v_cndmask_b32_dpp v112, v208, v248, vcc row_ror:8 row_mask:0xf bank_mask:0xf
	v_cndmask_b32_dpp v113, v209, v249, vcc row_ror:8 row_mask:0xf bank_mask:0xf
	s_not_b64 vcc, s[6:7]
	v_cndmask_b32_dpp v114, v0, v4, vcc row_ror:8 row_mask:0xf bank_mask:0xf
	v_cndmask_b32_dpp v115, v1, v5, vcc row_ror:8 row_mask:0xf bank_mask:0xf
	v_cndmask_b32_dpp v116, v2, v6, vcc row_ror:8 row_mask:0xf bank_mask:0xf
	v_cndmask_b32_dpp v117, v3, v7, vcc row_ror:8 row_mask:0xf bank_mask:0xf
	v_cndmask_b32_dpp v106, v246, v250, vcc row_ror:8 row_mask:0xf bank_mask:0xf
	v_cndmask_b32_dpp v107, v247, v251, vcc row_ror:8 row_mask:0xf bank_mask:0xf
	v_cndmask_b32_dpp v108, v248, v208, vcc row_ror:8 row_mask:0xf bank_mask:0xf
	v_cndmask_b32_dpp v109, v249, v209, vcc row_ror:8 row_mask:0xf bank_mask:0xf
	global_store_dwordx4 v171, v[118:121], s[2:3]
	global_store_dwordx4 v171, v[114:117], s[18:19]
	global_store_dwordx4 v171, v[110:113], s[78:79]
	global_store_dwordx4 v171, v[106:109], s[22:23]
	s_waitcnt vmcnt(12)
	s_mov_b64 vcc, s[6:7]
	v_cndmask_b32_dpp v0, v242, v238, vcc row_ror:8 row_mask:0xf bank_mask:0xf
	v_cndmask_b32_dpp v1, v243, v239, vcc row_ror:8 row_mask:0xf bank_mask:0xf
	v_cndmask_b32_dpp v2, v244, v240, vcc row_ror:8 row_mask:0xf bank_mask:0xf
	v_cndmask_b32_dpp v3, v245, v241, vcc row_ror:8 row_mask:0xf bank_mask:0xf
	s_not_b64 vcc, s[6:7]
	v_cndmask_b32_dpp v4, v238, v242, vcc row_ror:8 row_mask:0xf bank_mask:0xf
	v_cndmask_b32_dpp v5, v239, v243, vcc row_ror:8 row_mask:0xf bank_mask:0xf
	v_cndmask_b32_dpp v6, v240, v244, vcc row_ror:8 row_mask:0xf bank_mask:0xf
	v_cndmask_b32_dpp v7, v241, v245, vcc row_ror:8 row_mask:0xf bank_mask:0xf
	s_add_u32 s14, s14, 0x8000
	s_addc_u32 s15, s15, 0
	s_add_u32 s12, s12, 0x8000
	s_addc_u32 s13, s13, 0
	global_load_dwordx4 v[238:241], v171, s[14:15]
	global_load_dwordx4 v[242:245], v171, s[12:13]
	v_lshlrev_b32_e32 v246, 16, v0
	v_and_b32_e32 v247, 0xffff0000, v0
	v_pk_fma_f32 v[102:103], v[102:103], v[142:143], v[246:247]
	v_lshlrev_b32_e32 v248, 16, v1
	v_and_b32_e32 v249, 0xffff0000, v1
	v_pk_fma_f32 v[104:105], v[104:105], v[144:145], v[248:249]
	v_lshlrev_b32_e32 v250, 16, v2
	v_and_b32_e32 v251, 0xffff0000, v2
	v_pk_fma_f32 v[98:99], v[98:99], v[150:151], v[250:251]
	v_lshlrev_b32_e32 v208, 16, v3
	v_and_b32_e32 v209, 0xffff0000, v3
	v_pk_fma_f32 v[100:101], v[100:101], v[152:153], v[208:209]
	v_lshlrev_b32_e32 v246, 16, v4
	v_and_b32_e32 v247, 0xffff0000, v4
	v_pk_fma_f32 v[92:93], v[92:93], v[138:139], v[246:247]
	v_lshlrev_b32_e32 v248, 16, v5
	v_and_b32_e32 v249, 0xffff0000, v5
	v_pk_fma_f32 v[94:95], v[94:95], v[140:141], v[248:249]
	v_lshlrev_b32_e32 v250, 16, v6
	v_and_b32_e32 v251, 0xffff0000, v6
	v_pk_fma_f32 v[88:89], v[88:89], v[146:147], v[250:251]
	v_lshlrev_b32_e32 v208, 16, v7
	v_and_b32_e32 v209, 0xffff0000, v7
	v_pk_fma_f32 v[90:91], v[90:91], v[148:149], v[208:209]
	v_cvt_pk_bf16_f32 v0, v102, v103
	v_cvt_pk_bf16_f32 v1, v104, v105
	v_cvt_pk_bf16_f32 v2, v98, v99
	v_cvt_pk_bf16_f32 v3, v100, v101
	v_cvt_pk_bf16_f32 v4, v92, v93
	v_cvt_pk_bf16_f32 v5, v94, v95
	v_cvt_pk_bf16_f32 v6, v88, v89
	v_cvt_pk_bf16_f32 v7, v90, v91
	v_mul_f32_e32 v246, v103, v103
	v_mul_f32_e32 v248, v105, v105
	v_fmac_f32_e32 v246, v102, v102
	v_fmac_f32_e32 v248, v104, v104
	v_add_f32_e32 v246, v246, v248
	v_mul_f32_e32 v248, v99, v99
	v_fmac_f32_e32 v248, v98, v98
	v_add_f32_e32 v246, v246, v248
	v_mul_f32_e32 v248, v101, v101
	v_fmac_f32_e32 v248, v100, v100
	v_add_f32_e32 v246, v248, v246
	v_mul_f32_e32 v247, v93, v93
	v_mul_f32_e32 v248, v95, v95
	v_fmac_f32_e32 v247, v92, v92
	v_fmac_f32_e32 v248, v94, v94
	v_add_f32_e32 v247, v247, v248
	v_mul_f32_e32 v248, v89, v89
	v_fmac_f32_e32 v248, v88, v88
	v_add_f32_e32 v247, v247, v248
	v_mul_f32_e32 v248, v91, v91
	v_fmac_f32_e32 v248, v90, v90
	v_add_f32_e32 v247, v248, v247
	v_add_f32_e32 v246, v246, v247
	v_mov_b32_e32 v247, v246
	s_nop 1
	v_permlane16_swap_b32_e32 v246, v247
	s_nop 1
	v_add_f32_e32 v246, v246, v247
	v_mov_b32_e32 v247, v246
	s_nop 1
	v_permlane32_swap_b32_e32 v246, v247
	v_add_u32_e32 v248, s8, v223
	s_nop 0
	v_add_f32_e32 v246, v246, v247
	s_mov_b64 exec, s[44:45]
	ds_write_b32 v248, v246 offset:512
	s_mov_b64 exec, -1
	v_pk_mul_f32 v[102:103], v[180:181], v[102:103]
	v_pk_mul_f32 v[104:105], v[182:183], v[104:105]
	v_pk_mul_f32 v[98:99], v[184:185], v[98:99]
	v_pk_mul_f32 v[100:101], v[186:187], v[100:101]
	v_pk_mul_f32 v[92:93], v[188:189], v[92:93]
	v_pk_mul_f32 v[94:95], v[190:191], v[94:95]
	v_pk_mul_f32 v[88:89], v[192:193], v[88:89]
	v_pk_mul_f32 v[90:91], v[194:195], v[90:91]
	v_cvt_pk_bf16_f32 v246, v102, v103
	v_cvt_pk_bf16_f32 v247, v104, v105
	v_cvt_pk_bf16_f32 v248, v98, v99
	v_cvt_pk_bf16_f32 v249, v100, v101
	v_cvt_pk_bf16_f32 v250, v92, v93
	v_cvt_pk_bf16_f32 v251, v94, v95
	v_cvt_pk_bf16_f32 v208, v88, v89
	v_cvt_pk_bf16_f32 v209, v90, v91
	s_add_u32 s2, s2, 0x8000
	s_addc_u32 s3, s3, 0
	s_add_u32 s18, s18, 0x8000
	s_addc_u32 s19, s19, 0
	s_add_u32 s78, s78, 0x8000
	s_addc_u32 s79, s79, 0
	s_add_u32 s22, s22, 0x8000
	s_addc_u32 s23, s23, 0
	s_mov_b64 vcc, s[6:7]
	v_cndmask_b32_dpp v102, v4, v0, vcc row_ror:8 row_mask:0xf bank_mask:0xf
	v_cndmask_b32_dpp v103, v5, v1, vcc row_ror:8 row_mask:0xf bank_mask:0xf
	v_cndmask_b32_dpp v104, v6, v2, vcc row_ror:8 row_mask:0xf bank_mask:0xf
	v_cndmask_b32_dpp v105, v7, v3, vcc row_ror:8 row_mask:0xf bank_mask:0xf
	v_cndmask_b32_dpp v92, v250, v246, vcc row_ror:8 row_mask:0xf bank_mask:0xf
	v_cndmask_b32_dpp v93, v251, v247, vcc row_ror:8 row_mask:0xf bank_mask:0xf
	v_cndmask_b32_dpp v94, v208, v248, vcc row_ror:8 row_mask:0xf bank_mask:0xf
	v_cndmask_b32_dpp v95, v209, v249, vcc row_ror:8 row_mask:0xf bank_mask:0xf
	s_not_b64 vcc, s[6:7]
	v_cndmask_b32_dpp v98, v0, v4, vcc row_ror:8 row_mask:0xf bank_mask:0xf
	v_cndmask_b32_dpp v99, v1, v5, vcc row_ror:8 row_mask:0xf bank_mask:0xf
	v_cndmask_b32_dpp v100, v2, v6, vcc row_ror:8 row_mask:0xf bank_mask:0xf
	v_cndmask_b32_dpp v101, v3, v7, vcc row_ror:8 row_mask:0xf bank_mask:0xf
	v_cndmask_b32_dpp v88, v246, v250, vcc row_ror:8 row_mask:0xf bank_mask:0xf
	v_cndmask_b32_dpp v89, v247, v251, vcc row_ror:8 row_mask:0xf bank_mask:0xf
	v_cndmask_b32_dpp v90, v248, v208, vcc row_ror:8 row_mask:0xf bank_mask:0xf
	v_cndmask_b32_dpp v91, v249, v209, vcc row_ror:8 row_mask:0xf bank_mask:0xf
	global_store_dwordx4 v171, v[102:105], s[2:3]
	global_store_dwordx4 v171, v[98:101], s[18:19]
	global_store_dwordx4 v171, v[92:95], s[78:79]
	global_store_dwordx4 v171, v[88:91], s[22:23]
	s_waitcnt vmcnt(16)
	s_mov_b64 vcc, s[6:7]
	v_cndmask_b32_dpp v0, v200, v196, vcc row_ror:8 row_mask:0xf bank_mask:0xf
	v_cndmask_b32_dpp v1, v201, v197, vcc row_ror:8 row_mask:0xf bank_mask:0xf
	v_cndmask_b32_dpp v2, v202, v198, vcc row_ror:8 row_mask:0xf bank_mask:0xf
	v_cndmask_b32_dpp v3, v203, v199, vcc row_ror:8 row_mask:0xf bank_mask:0xf
	s_not_b64 vcc, s[6:7]
	v_cndmask_b32_dpp v4, v196, v200, vcc row_ror:8 row_mask:0xf bank_mask:0xf
	v_cndmask_b32_dpp v5, v197, v201, vcc row_ror:8 row_mask:0xf bank_mask:0xf
	v_cndmask_b32_dpp v6, v198, v202, vcc row_ror:8 row_mask:0xf bank_mask:0xf
	v_cndmask_b32_dpp v7, v199, v203, vcc row_ror:8 row_mask:0xf bank_mask:0xf
	s_add_u32 s14, s14, 0x8000
	s_addc_u32 s15, s15, 0
	s_add_u32 s12, s12, 0x8000
	s_addc_u32 s13, s13, 0
	global_load_dwordx4 v[196:199], v171, s[14:15]
	global_load_dwordx4 v[200:203], v171, s[12:13]
	v_lshlrev_b32_e32 v246, 16, v0
	v_and_b32_e32 v247, 0xffff0000, v0
	v_pk_fma_f32 v[84:85], v[84:85], v[142:143], v[246:247]
	v_lshlrev_b32_e32 v248, 16, v1
	v_and_b32_e32 v249, 0xffff0000, v1
	v_pk_fma_f32 v[86:87], v[86:87], v[144:145], v[248:249]
	v_lshlrev_b32_e32 v250, 16, v2
	v_and_b32_e32 v251, 0xffff0000, v2
	v_pk_fma_f32 v[80:81], v[80:81], v[150:151], v[250:251]
	v_lshlrev_b32_e32 v208, 16, v3
	v_and_b32_e32 v209, 0xffff0000, v3
	v_pk_fma_f32 v[82:83], v[82:83], v[152:153], v[208:209]
	v_lshlrev_b32_e32 v246, 16, v4
	v_and_b32_e32 v247, 0xffff0000, v4
	v_pk_fma_f32 v[76:77], v[76:77], v[138:139], v[246:247]
	v_lshlrev_b32_e32 v248, 16, v5
	v_and_b32_e32 v249, 0xffff0000, v5
	v_pk_fma_f32 v[78:79], v[78:79], v[140:141], v[248:249]
	v_lshlrev_b32_e32 v250, 16, v6
	v_and_b32_e32 v251, 0xffff0000, v6
	v_pk_fma_f32 v[72:73], v[72:73], v[146:147], v[250:251]
	v_lshlrev_b32_e32 v208, 16, v7
	v_and_b32_e32 v209, 0xffff0000, v7
	v_pk_fma_f32 v[74:75], v[74:75], v[148:149], v[208:209]
	v_cvt_pk_bf16_f32 v0, v84, v85
	v_cvt_pk_bf16_f32 v1, v86, v87
	v_cvt_pk_bf16_f32 v2, v80, v81
	v_cvt_pk_bf16_f32 v3, v82, v83
	v_cvt_pk_bf16_f32 v4, v76, v77
	v_cvt_pk_bf16_f32 v5, v78, v79
	v_cvt_pk_bf16_f32 v6, v72, v73
	v_cvt_pk_bf16_f32 v7, v74, v75
	v_mul_f32_e32 v246, v85, v85
	v_mul_f32_e32 v248, v87, v87
	v_fmac_f32_e32 v246, v84, v84
	v_fmac_f32_e32 v248, v86, v86
	v_add_f32_e32 v246, v246, v248
	v_mul_f32_e32 v248, v81, v81
	v_fmac_f32_e32 v248, v80, v80
	v_add_f32_e32 v246, v246, v248
	v_mul_f32_e32 v248, v83, v83
	v_fmac_f32_e32 v248, v82, v82
	v_add_f32_e32 v246, v248, v246
	v_mul_f32_e32 v247, v77, v77
	v_mul_f32_e32 v248, v79, v79
	v_fmac_f32_e32 v247, v76, v76
	v_fmac_f32_e32 v248, v78, v78
	v_add_f32_e32 v247, v247, v248
	v_mul_f32_e32 v248, v73, v73
	v_fmac_f32_e32 v248, v72, v72
	v_add_f32_e32 v247, v247, v248
	v_mul_f32_e32 v248, v75, v75
	v_fmac_f32_e32 v248, v74, v74
	v_add_f32_e32 v247, v248, v247
	v_add_f32_e32 v246, v246, v247
	v_mov_b32_e32 v247, v246
	s_nop 1
	v_permlane16_swap_b32_e32 v246, v247
	s_nop 1
	v_add_f32_e32 v246, v246, v247
	v_mov_b32_e32 v247, v246
	s_nop 1
	v_permlane32_swap_b32_e32 v246, v247
	v_add_u32_e32 v248, s8, v223
	s_nop 0
	v_add_f32_e32 v246, v246, v247
	s_mov_b64 exec, s[44:45]
	ds_write_b32 v248, v246 offset:768
	s_mov_b64 exec, -1
	v_pk_mul_f32 v[84:85], v[180:181], v[84:85]
	v_pk_mul_f32 v[86:87], v[182:183], v[86:87]
	v_pk_mul_f32 v[80:81], v[184:185], v[80:81]
	v_pk_mul_f32 v[82:83], v[186:187], v[82:83]
	v_pk_mul_f32 v[76:77], v[188:189], v[76:77]
	v_pk_mul_f32 v[78:79], v[190:191], v[78:79]
	v_pk_mul_f32 v[72:73], v[192:193], v[72:73]
	v_pk_mul_f32 v[74:75], v[194:195], v[74:75]
	v_cvt_pk_bf16_f32 v246, v84, v85
	v_cvt_pk_bf16_f32 v247, v86, v87
	v_cvt_pk_bf16_f32 v248, v80, v81
	v_cvt_pk_bf16_f32 v249, v82, v83
	v_cvt_pk_bf16_f32 v250, v76, v77
	v_cvt_pk_bf16_f32 v251, v78, v79
	v_cvt_pk_bf16_f32 v208, v72, v73
	v_cvt_pk_bf16_f32 v209, v74, v75
	s_add_u32 s2, s2, 0x8000
	s_addc_u32 s3, s3, 0
	s_add_u32 s18, s18, 0x8000
	s_addc_u32 s19, s19, 0
	s_add_u32 s78, s78, 0x8000
	s_addc_u32 s79, s79, 0
	s_add_u32 s22, s22, 0x8000
	s_addc_u32 s23, s23, 0
	s_mov_b64 vcc, s[6:7]
	v_cndmask_b32_dpp v84, v4, v0, vcc row_ror:8 row_mask:0xf bank_mask:0xf
	v_cndmask_b32_dpp v85, v5, v1, vcc row_ror:8 row_mask:0xf bank_mask:0xf
	v_cndmask_b32_dpp v86, v6, v2, vcc row_ror:8 row_mask:0xf bank_mask:0xf
	v_cndmask_b32_dpp v87, v7, v3, vcc row_ror:8 row_mask:0xf bank_mask:0xf
	v_cndmask_b32_dpp v76, v250, v246, vcc row_ror:8 row_mask:0xf bank_mask:0xf
	v_cndmask_b32_dpp v77, v251, v247, vcc row_ror:8 row_mask:0xf bank_mask:0xf
	v_cndmask_b32_dpp v78, v208, v248, vcc row_ror:8 row_mask:0xf bank_mask:0xf
	v_cndmask_b32_dpp v79, v209, v249, vcc row_ror:8 row_mask:0xf bank_mask:0xf
	s_not_b64 vcc, s[6:7]
	v_cndmask_b32_dpp v80, v0, v4, vcc row_ror:8 row_mask:0xf bank_mask:0xf
	v_cndmask_b32_dpp v81, v1, v5, vcc row_ror:8 row_mask:0xf bank_mask:0xf
	v_cndmask_b32_dpp v82, v2, v6, vcc row_ror:8 row_mask:0xf bank_mask:0xf
	v_cndmask_b32_dpp v83, v3, v7, vcc row_ror:8 row_mask:0xf bank_mask:0xf
	v_cndmask_b32_dpp v72, v246, v250, vcc row_ror:8 row_mask:0xf bank_mask:0xf
	v_cndmask_b32_dpp v73, v247, v251, vcc row_ror:8 row_mask:0xf bank_mask:0xf
	v_cndmask_b32_dpp v74, v248, v208, vcc row_ror:8 row_mask:0xf bank_mask:0xf
	v_cndmask_b32_dpp v75, v249, v209, vcc row_ror:8 row_mask:0xf bank_mask:0xf
	global_store_dwordx4 v171, v[84:87], s[2:3]
	global_store_dwordx4 v171, v[80:83], s[18:19]
	global_store_dwordx4 v171, v[76:79], s[78:79]
	global_store_dwordx4 v171, v[72:75], s[22:23]
	s_waitcnt vmcnt(16)
	s_mov_b64 vcc, s[6:7]
	v_cndmask_b32_dpp v0, v234, v204, vcc row_ror:8 row_mask:0xf bank_mask:0xf
	v_cndmask_b32_dpp v1, v235, v205, vcc row_ror:8 row_mask:0xf bank_mask:0xf
	v_cndmask_b32_dpp v2, v236, v206, vcc row_ror:8 row_mask:0xf bank_mask:0xf
	v_cndmask_b32_dpp v3, v237, v207, vcc row_ror:8 row_mask:0xf bank_mask:0xf
	s_not_b64 vcc, s[6:7]
	v_cndmask_b32_dpp v4, v204, v234, vcc row_ror:8 row_mask:0xf bank_mask:0xf
	v_cndmask_b32_dpp v5, v205, v235, vcc row_ror:8 row_mask:0xf bank_mask:0xf
	v_cndmask_b32_dpp v6, v206, v236, vcc row_ror:8 row_mask:0xf bank_mask:0xf
	v_cndmask_b32_dpp v7, v207, v237, vcc row_ror:8 row_mask:0xf bank_mask:0xf
	s_add_u32 s14, s14, 0x8000
	s_addc_u32 s15, s15, 0
	s_add_u32 s12, s12, 0x8000
	s_addc_u32 s13, s13, 0
	global_load_dwordx4 v[204:207], v171, s[14:15]
	global_load_dwordx4 v[234:237], v171, s[12:13]
	v_lshlrev_b32_e32 v246, 16, v0
	v_and_b32_e32 v247, 0xffff0000, v0
	v_pk_fma_f32 v[68:69], v[68:69], v[142:143], v[246:247]
	v_lshlrev_b32_e32 v248, 16, v1
	v_and_b32_e32 v249, 0xffff0000, v1
	v_pk_fma_f32 v[70:71], v[70:71], v[144:145], v[248:249]
	v_lshlrev_b32_e32 v250, 16, v2
	v_and_b32_e32 v251, 0xffff0000, v2
	v_pk_fma_f32 v[64:65], v[64:65], v[150:151], v[250:251]
	v_lshlrev_b32_e32 v208, 16, v3
	v_and_b32_e32 v209, 0xffff0000, v3
	v_pk_fma_f32 v[66:67], v[66:67], v[152:153], v[208:209]
	v_lshlrev_b32_e32 v246, 16, v4
	v_and_b32_e32 v247, 0xffff0000, v4
	v_pk_fma_f32 v[60:61], v[60:61], v[138:139], v[246:247]
	v_lshlrev_b32_e32 v248, 16, v5
	v_and_b32_e32 v249, 0xffff0000, v5
	v_pk_fma_f32 v[62:63], v[62:63], v[140:141], v[248:249]
	v_lshlrev_b32_e32 v250, 16, v6
	v_and_b32_e32 v251, 0xffff0000, v6
	v_pk_fma_f32 v[56:57], v[56:57], v[146:147], v[250:251]
	v_lshlrev_b32_e32 v208, 16, v7
	v_and_b32_e32 v209, 0xffff0000, v7
	v_pk_fma_f32 v[58:59], v[58:59], v[148:149], v[208:209]
	v_cvt_pk_bf16_f32 v0, v68, v69
	v_cvt_pk_bf16_f32 v1, v70, v71
	v_cvt_pk_bf16_f32 v2, v64, v65
	v_cvt_pk_bf16_f32 v3, v66, v67
	v_cvt_pk_bf16_f32 v4, v60, v61
	v_cvt_pk_bf16_f32 v5, v62, v63
	v_cvt_pk_bf16_f32 v6, v56, v57
	v_cvt_pk_bf16_f32 v7, v58, v59
	v_mul_f32_e32 v246, v69, v69
	v_mul_f32_e32 v248, v71, v71
	v_fmac_f32_e32 v246, v68, v68
	v_fmac_f32_e32 v248, v70, v70
	v_add_f32_e32 v246, v246, v248
	v_mul_f32_e32 v248, v65, v65
	v_fmac_f32_e32 v248, v64, v64
	v_add_f32_e32 v246, v246, v248
	v_mul_f32_e32 v248, v67, v67
	v_fmac_f32_e32 v248, v66, v66
	v_add_f32_e32 v246, v248, v246
	v_mul_f32_e32 v247, v61, v61
	v_mul_f32_e32 v248, v63, v63
	v_fmac_f32_e32 v247, v60, v60
	v_fmac_f32_e32 v248, v62, v62
	v_add_f32_e32 v247, v247, v248
	v_mul_f32_e32 v248, v57, v57
	v_fmac_f32_e32 v248, v56, v56
	v_add_f32_e32 v247, v247, v248
	v_mul_f32_e32 v248, v59, v59
	v_fmac_f32_e32 v248, v58, v58
	v_add_f32_e32 v247, v248, v247
	v_add_f32_e32 v246, v246, v247
	v_mov_b32_e32 v247, v246
	s_nop 1
	v_permlane16_swap_b32_e32 v246, v247
	s_nop 1
	v_add_f32_e32 v246, v246, v247
	v_mov_b32_e32 v247, v246
	s_nop 1
	v_permlane32_swap_b32_e32 v246, v247
	v_add_u32_e32 v248, s8, v223
	s_nop 0
	v_add_f32_e32 v246, v246, v247
	s_mov_b64 exec, s[44:45]
	ds_write_b32 v248, v246 offset:2048
	s_mov_b64 exec, -1
	v_pk_mul_f32 v[68:69], v[180:181], v[68:69]
	v_pk_mul_f32 v[70:71], v[182:183], v[70:71]
	v_pk_mul_f32 v[64:65], v[184:185], v[64:65]
	v_pk_mul_f32 v[66:67], v[186:187], v[66:67]
	v_pk_mul_f32 v[60:61], v[188:189], v[60:61]
	v_pk_mul_f32 v[62:63], v[190:191], v[62:63]
	v_pk_mul_f32 v[56:57], v[192:193], v[56:57]
	v_pk_mul_f32 v[58:59], v[194:195], v[58:59]
	v_cvt_pk_bf16_f32 v246, v68, v69
	v_cvt_pk_bf16_f32 v247, v70, v71
	v_cvt_pk_bf16_f32 v248, v64, v65
	v_cvt_pk_bf16_f32 v249, v66, v67
	v_cvt_pk_bf16_f32 v250, v60, v61
	v_cvt_pk_bf16_f32 v251, v62, v63
	v_cvt_pk_bf16_f32 v208, v56, v57
	v_cvt_pk_bf16_f32 v209, v58, v59
	s_add_u32 s2, s2, 0x28000
	s_addc_u32 s3, s3, 0
	s_add_u32 s18, s18, 0x28000
	s_addc_u32 s19, s19, 0
	s_add_u32 s78, s78, 0x28000
	s_addc_u32 s79, s79, 0
	s_add_u32 s22, s22, 0x28000
	s_addc_u32 s23, s23, 0
	s_mov_b64 vcc, s[6:7]
	v_cndmask_b32_dpp v68, v4, v0, vcc row_ror:8 row_mask:0xf bank_mask:0xf
	v_cndmask_b32_dpp v69, v5, v1, vcc row_ror:8 row_mask:0xf bank_mask:0xf
	v_cndmask_b32_dpp v70, v6, v2, vcc row_ror:8 row_mask:0xf bank_mask:0xf
	v_cndmask_b32_dpp v71, v7, v3, vcc row_ror:8 row_mask:0xf bank_mask:0xf
	v_cndmask_b32_dpp v60, v250, v246, vcc row_ror:8 row_mask:0xf bank_mask:0xf
	v_cndmask_b32_dpp v61, v251, v247, vcc row_ror:8 row_mask:0xf bank_mask:0xf
	v_cndmask_b32_dpp v62, v208, v248, vcc row_ror:8 row_mask:0xf bank_mask:0xf
	v_cndmask_b32_dpp v63, v209, v249, vcc row_ror:8 row_mask:0xf bank_mask:0xf
	s_not_b64 vcc, s[6:7]
	v_cndmask_b32_dpp v64, v0, v4, vcc row_ror:8 row_mask:0xf bank_mask:0xf
	v_cndmask_b32_dpp v65, v1, v5, vcc row_ror:8 row_mask:0xf bank_mask:0xf
	v_cndmask_b32_dpp v66, v2, v6, vcc row_ror:8 row_mask:0xf bank_mask:0xf
	v_cndmask_b32_dpp v67, v3, v7, vcc row_ror:8 row_mask:0xf bank_mask:0xf
	v_cndmask_b32_dpp v56, v246, v250, vcc row_ror:8 row_mask:0xf bank_mask:0xf
	v_cndmask_b32_dpp v57, v247, v251, vcc row_ror:8 row_mask:0xf bank_mask:0xf
	v_cndmask_b32_dpp v58, v248, v208, vcc row_ror:8 row_mask:0xf bank_mask:0xf
	v_cndmask_b32_dpp v59, v249, v209, vcc row_ror:8 row_mask:0xf bank_mask:0xf
	global_store_dwordx4 v171, v[68:71], s[2:3]
	global_store_dwordx4 v171, v[64:67], s[18:19]
	global_store_dwordx4 v171, v[60:63], s[78:79]
	global_store_dwordx4 v171, v[56:59], s[22:23]
	s_waitcnt vmcnt(16)
	s_mov_b64 vcc, s[6:7]
	v_cndmask_b32_dpp v0, v242, v238, vcc row_ror:8 row_mask:0xf bank_mask:0xf
	v_cndmask_b32_dpp v1, v243, v239, vcc row_ror:8 row_mask:0xf bank_mask:0xf
	v_cndmask_b32_dpp v2, v244, v240, vcc row_ror:8 row_mask:0xf bank_mask:0xf
	v_cndmask_b32_dpp v3, v245, v241, vcc row_ror:8 row_mask:0xf bank_mask:0xf
	s_not_b64 vcc, s[6:7]
	v_cndmask_b32_dpp v4, v238, v242, vcc row_ror:8 row_mask:0xf bank_mask:0xf
	v_cndmask_b32_dpp v5, v239, v243, vcc row_ror:8 row_mask:0xf bank_mask:0xf
	v_cndmask_b32_dpp v6, v240, v244, vcc row_ror:8 row_mask:0xf bank_mask:0xf
	v_cndmask_b32_dpp v7, v241, v245, vcc row_ror:8 row_mask:0xf bank_mask:0xf
	v_lshlrev_b32_e32 v246, 16, v0
	v_and_b32_e32 v247, 0xffff0000, v0
	v_pk_fma_f32 v[52:53], v[52:53], v[142:143], v[246:247]
	v_lshlrev_b32_e32 v248, 16, v1
	v_and_b32_e32 v249, 0xffff0000, v1
	v_pk_fma_f32 v[54:55], v[54:55], v[144:145], v[248:249]
	v_lshlrev_b32_e32 v250, 16, v2
	v_and_b32_e32 v251, 0xffff0000, v2
	v_pk_fma_f32 v[48:49], v[48:49], v[150:151], v[250:251]
	v_lshlrev_b32_e32 v208, 16, v3
	v_and_b32_e32 v209, 0xffff0000, v3
	v_pk_fma_f32 v[50:51], v[50:51], v[152:153], v[208:209]
	v_lshlrev_b32_e32 v246, 16, v4
	v_and_b32_e32 v247, 0xffff0000, v4
	v_pk_fma_f32 v[44:45], v[44:45], v[138:139], v[246:247]
	v_lshlrev_b32_e32 v248, 16, v5
	v_and_b32_e32 v249, 0xffff0000, v5
	v_pk_fma_f32 v[46:47], v[46:47], v[140:141], v[248:249]
	v_lshlrev_b32_e32 v250, 16, v6
	v_and_b32_e32 v251, 0xffff0000, v6
	v_pk_fma_f32 v[40:41], v[40:41], v[146:147], v[250:251]
	v_lshlrev_b32_e32 v208, 16, v7
	v_and_b32_e32 v209, 0xffff0000, v7
	v_pk_fma_f32 v[42:43], v[42:43], v[148:149], v[208:209]
	v_cvt_pk_bf16_f32 v0, v52, v53
	v_cvt_pk_bf16_f32 v1, v54, v55
	v_cvt_pk_bf16_f32 v2, v48, v49
	v_cvt_pk_bf16_f32 v3, v50, v51
	v_cvt_pk_bf16_f32 v4, v44, v45
	v_cvt_pk_bf16_f32 v5, v46, v47
	v_cvt_pk_bf16_f32 v6, v40, v41
	v_cvt_pk_bf16_f32 v7, v42, v43
	v_mul_f32_e32 v246, v53, v53
	v_mul_f32_e32 v248, v55, v55
	v_fmac_f32_e32 v246, v52, v52
	v_fmac_f32_e32 v248, v54, v54
	v_add_f32_e32 v246, v246, v248
	v_mul_f32_e32 v248, v49, v49
	v_fmac_f32_e32 v248, v48, v48
	v_add_f32_e32 v246, v246, v248
	v_mul_f32_e32 v248, v51, v51
	v_fmac_f32_e32 v248, v50, v50
	v_add_f32_e32 v246, v248, v246
	v_mul_f32_e32 v247, v45, v45
	v_mul_f32_e32 v248, v47, v47
	v_fmac_f32_e32 v247, v44, v44
	v_fmac_f32_e32 v248, v46, v46
	v_add_f32_e32 v247, v247, v248
	v_mul_f32_e32 v248, v41, v41
	v_fmac_f32_e32 v248, v40, v40
	v_add_f32_e32 v247, v247, v248
	v_mul_f32_e32 v248, v43, v43
	v_fmac_f32_e32 v248, v42, v42
	v_add_f32_e32 v247, v248, v247
	v_add_f32_e32 v246, v246, v247
	v_mov_b32_e32 v247, v246
	s_nop 1
	v_permlane16_swap_b32_e32 v246, v247
	s_nop 1
	v_add_f32_e32 v246, v246, v247
	v_mov_b32_e32 v247, v246
	s_nop 1
	v_permlane32_swap_b32_e32 v246, v247
	v_add_u32_e32 v248, s8, v223
	s_nop 0
	v_add_f32_e32 v246, v246, v247
	s_mov_b64 exec, s[44:45]
	ds_write_b32 v248, v246 offset:2304
	s_mov_b64 exec, -1
	v_pk_mul_f32 v[52:53], v[180:181], v[52:53]
	v_pk_mul_f32 v[54:55], v[182:183], v[54:55]
	v_pk_mul_f32 v[48:49], v[184:185], v[48:49]
	v_pk_mul_f32 v[50:51], v[186:187], v[50:51]
	v_pk_mul_f32 v[44:45], v[188:189], v[44:45]
	v_pk_mul_f32 v[46:47], v[190:191], v[46:47]
	v_pk_mul_f32 v[40:41], v[192:193], v[40:41]
	v_pk_mul_f32 v[42:43], v[194:195], v[42:43]
	v_cvt_pk_bf16_f32 v246, v52, v53
	v_cvt_pk_bf16_f32 v247, v54, v55
	v_cvt_pk_bf16_f32 v248, v48, v49
	v_cvt_pk_bf16_f32 v249, v50, v51
	v_cvt_pk_bf16_f32 v250, v44, v45
	v_cvt_pk_bf16_f32 v251, v46, v47
	v_cvt_pk_bf16_f32 v208, v40, v41
	v_cvt_pk_bf16_f32 v209, v42, v43
	s_add_u32 s2, s2, 0x8000
	s_addc_u32 s3, s3, 0
	s_add_u32 s18, s18, 0x8000
	s_addc_u32 s19, s19, 0
	s_add_u32 s78, s78, 0x8000
	s_addc_u32 s79, s79, 0
	s_add_u32 s22, s22, 0x8000
	s_addc_u32 s23, s23, 0
	s_mov_b64 vcc, s[6:7]
	v_cndmask_b32_dpp v52, v4, v0, vcc row_ror:8 row_mask:0xf bank_mask:0xf
	v_cndmask_b32_dpp v53, v5, v1, vcc row_ror:8 row_mask:0xf bank_mask:0xf
	v_cndmask_b32_dpp v54, v6, v2, vcc row_ror:8 row_mask:0xf bank_mask:0xf
	v_cndmask_b32_dpp v55, v7, v3, vcc row_ror:8 row_mask:0xf bank_mask:0xf
	v_cndmask_b32_dpp v44, v250, v246, vcc row_ror:8 row_mask:0xf bank_mask:0xf
	v_cndmask_b32_dpp v45, v251, v247, vcc row_ror:8 row_mask:0xf bank_mask:0xf
	v_cndmask_b32_dpp v46, v208, v248, vcc row_ror:8 row_mask:0xf bank_mask:0xf
	v_cndmask_b32_dpp v47, v209, v249, vcc row_ror:8 row_mask:0xf bank_mask:0xf
	s_not_b64 vcc, s[6:7]
	v_cndmask_b32_dpp v48, v0, v4, vcc row_ror:8 row_mask:0xf bank_mask:0xf
	v_cndmask_b32_dpp v49, v1, v5, vcc row_ror:8 row_mask:0xf bank_mask:0xf
	v_cndmask_b32_dpp v50, v2, v6, vcc row_ror:8 row_mask:0xf bank_mask:0xf
	v_cndmask_b32_dpp v51, v3, v7, vcc row_ror:8 row_mask:0xf bank_mask:0xf
	v_cndmask_b32_dpp v40, v246, v250, vcc row_ror:8 row_mask:0xf bank_mask:0xf
	v_cndmask_b32_dpp v41, v247, v251, vcc row_ror:8 row_mask:0xf bank_mask:0xf
	v_cndmask_b32_dpp v42, v248, v208, vcc row_ror:8 row_mask:0xf bank_mask:0xf
	v_cndmask_b32_dpp v43, v249, v209, vcc row_ror:8 row_mask:0xf bank_mask:0xf
	global_store_dwordx4 v171, v[52:55], s[2:3]
	global_store_dwordx4 v171, v[48:51], s[18:19]
	global_store_dwordx4 v171, v[44:47], s[78:79]
	global_store_dwordx4 v171, v[40:43], s[22:23]
	s_waitcnt vmcnt(14)
	s_mov_b64 vcc, s[6:7]
	v_cndmask_b32_dpp v0, v200, v196, vcc row_ror:8 row_mask:0xf bank_mask:0xf
	v_cndmask_b32_dpp v1, v201, v197, vcc row_ror:8 row_mask:0xf bank_mask:0xf
	v_cndmask_b32_dpp v2, v202, v198, vcc row_ror:8 row_mask:0xf bank_mask:0xf
	v_cndmask_b32_dpp v3, v203, v199, vcc row_ror:8 row_mask:0xf bank_mask:0xf
	s_not_b64 vcc, s[6:7]
	v_cndmask_b32_dpp v4, v196, v200, vcc row_ror:8 row_mask:0xf bank_mask:0xf
	v_cndmask_b32_dpp v5, v197, v201, vcc row_ror:8 row_mask:0xf bank_mask:0xf
	v_cndmask_b32_dpp v6, v198, v202, vcc row_ror:8 row_mask:0xf bank_mask:0xf
	v_cndmask_b32_dpp v7, v199, v203, vcc row_ror:8 row_mask:0xf bank_mask:0xf
	v_lshlrev_b32_e32 v246, 16, v0
	v_and_b32_e32 v247, 0xffff0000, v0
	v_pk_fma_f32 v[36:37], v[36:37], v[142:143], v[246:247]
	v_lshlrev_b32_e32 v248, 16, v1
	v_and_b32_e32 v249, 0xffff0000, v1
	v_pk_fma_f32 v[38:39], v[38:39], v[144:145], v[248:249]
	v_lshlrev_b32_e32 v250, 16, v2
	v_and_b32_e32 v251, 0xffff0000, v2
	v_pk_fma_f32 v[32:33], v[32:33], v[150:151], v[250:251]
	v_lshlrev_b32_e32 v208, 16, v3
	v_and_b32_e32 v209, 0xffff0000, v3
	v_pk_fma_f32 v[34:35], v[34:35], v[152:153], v[208:209]
	v_lshlrev_b32_e32 v246, 16, v4
	v_and_b32_e32 v247, 0xffff0000, v4
	v_pk_fma_f32 v[28:29], v[28:29], v[138:139], v[246:247]
	v_lshlrev_b32_e32 v248, 16, v5
	v_and_b32_e32 v249, 0xffff0000, v5
	v_pk_fma_f32 v[30:31], v[30:31], v[140:141], v[248:249]
	v_lshlrev_b32_e32 v250, 16, v6
	v_and_b32_e32 v251, 0xffff0000, v6
	v_pk_fma_f32 v[24:25], v[24:25], v[146:147], v[250:251]
	v_lshlrev_b32_e32 v208, 16, v7
	v_and_b32_e32 v209, 0xffff0000, v7
	v_pk_fma_f32 v[26:27], v[26:27], v[148:149], v[208:209]
	v_cvt_pk_bf16_f32 v0, v36, v37
	v_cvt_pk_bf16_f32 v1, v38, v39
	v_cvt_pk_bf16_f32 v2, v32, v33
	v_cvt_pk_bf16_f32 v3, v34, v35
	v_cvt_pk_bf16_f32 v4, v28, v29
	v_cvt_pk_bf16_f32 v5, v30, v31
	v_cvt_pk_bf16_f32 v6, v24, v25
	v_cvt_pk_bf16_f32 v7, v26, v27
	v_mul_f32_e32 v246, v37, v37
	v_mul_f32_e32 v248, v39, v39
	v_fmac_f32_e32 v246, v36, v36
	v_fmac_f32_e32 v248, v38, v38
	v_add_f32_e32 v246, v246, v248
	v_mul_f32_e32 v248, v33, v33
	v_fmac_f32_e32 v248, v32, v32
	v_add_f32_e32 v246, v246, v248
	v_mul_f32_e32 v248, v35, v35
	v_fmac_f32_e32 v248, v34, v34
	v_add_f32_e32 v246, v248, v246
	v_mul_f32_e32 v247, v29, v29
	v_mul_f32_e32 v248, v31, v31
	v_fmac_f32_e32 v247, v28, v28
	v_fmac_f32_e32 v248, v30, v30
	v_add_f32_e32 v247, v247, v248
	v_mul_f32_e32 v248, v25, v25
	v_fmac_f32_e32 v248, v24, v24
	v_add_f32_e32 v247, v247, v248
	v_mul_f32_e32 v248, v27, v27
	v_fmac_f32_e32 v248, v26, v26
	v_add_f32_e32 v247, v248, v247
	v_add_f32_e32 v246, v246, v247
	v_mov_b32_e32 v247, v246
	s_nop 1
	v_permlane16_swap_b32_e32 v246, v247
	s_nop 1
	v_add_f32_e32 v246, v246, v247
	v_mov_b32_e32 v247, v246
	s_nop 1
	v_permlane32_swap_b32_e32 v246, v247
	v_add_u32_e32 v248, s8, v223
	s_nop 0
	v_add_f32_e32 v246, v246, v247
	s_mov_b64 exec, s[44:45]
	ds_write_b32 v248, v246 offset:2560
	s_mov_b64 exec, -1
	v_pk_mul_f32 v[36:37], v[180:181], v[36:37]
	v_pk_mul_f32 v[38:39], v[182:183], v[38:39]
	v_pk_mul_f32 v[32:33], v[184:185], v[32:33]
	v_pk_mul_f32 v[34:35], v[186:187], v[34:35]
	v_pk_mul_f32 v[28:29], v[188:189], v[28:29]
	v_pk_mul_f32 v[30:31], v[190:191], v[30:31]
	v_pk_mul_f32 v[24:25], v[192:193], v[24:25]
	v_pk_mul_f32 v[26:27], v[194:195], v[26:27]
	v_cvt_pk_bf16_f32 v246, v36, v37
	v_cvt_pk_bf16_f32 v247, v38, v39
	v_cvt_pk_bf16_f32 v248, v32, v33
	v_cvt_pk_bf16_f32 v249, v34, v35
	v_cvt_pk_bf16_f32 v250, v28, v29
	v_cvt_pk_bf16_f32 v251, v30, v31
	v_cvt_pk_bf16_f32 v208, v24, v25
	v_cvt_pk_bf16_f32 v209, v26, v27
	s_add_u32 s2, s2, 0x8000
	s_addc_u32 s3, s3, 0
	s_add_u32 s18, s18, 0x8000
	s_addc_u32 s19, s19, 0
	s_add_u32 s78, s78, 0x8000
	s_addc_u32 s79, s79, 0
	s_add_u32 s22, s22, 0x8000
	s_addc_u32 s23, s23, 0
	s_mov_b64 vcc, s[6:7]
	v_cndmask_b32_dpp v36, v4, v0, vcc row_ror:8 row_mask:0xf bank_mask:0xf
	v_cndmask_b32_dpp v37, v5, v1, vcc row_ror:8 row_mask:0xf bank_mask:0xf
	v_cndmask_b32_dpp v38, v6, v2, vcc row_ror:8 row_mask:0xf bank_mask:0xf
	v_cndmask_b32_dpp v39, v7, v3, vcc row_ror:8 row_mask:0xf bank_mask:0xf
	v_cndmask_b32_dpp v28, v250, v246, vcc row_ror:8 row_mask:0xf bank_mask:0xf
	v_cndmask_b32_dpp v29, v251, v247, vcc row_ror:8 row_mask:0xf bank_mask:0xf
	v_cndmask_b32_dpp v30, v208, v248, vcc row_ror:8 row_mask:0xf bank_mask:0xf
	v_cndmask_b32_dpp v31, v209, v249, vcc row_ror:8 row_mask:0xf bank_mask:0xf
	s_not_b64 vcc, s[6:7]
	v_cndmask_b32_dpp v32, v0, v4, vcc row_ror:8 row_mask:0xf bank_mask:0xf
	v_cndmask_b32_dpp v33, v1, v5, vcc row_ror:8 row_mask:0xf bank_mask:0xf
	v_cndmask_b32_dpp v34, v2, v6, vcc row_ror:8 row_mask:0xf bank_mask:0xf
	v_cndmask_b32_dpp v35, v3, v7, vcc row_ror:8 row_mask:0xf bank_mask:0xf
	v_cndmask_b32_dpp v24, v246, v250, vcc row_ror:8 row_mask:0xf bank_mask:0xf
	v_cndmask_b32_dpp v25, v247, v251, vcc row_ror:8 row_mask:0xf bank_mask:0xf
	v_cndmask_b32_dpp v26, v248, v208, vcc row_ror:8 row_mask:0xf bank_mask:0xf
	v_cndmask_b32_dpp v27, v249, v209, vcc row_ror:8 row_mask:0xf bank_mask:0xf
	global_store_dwordx4 v171, v[36:39], s[2:3]
	global_store_dwordx4 v171, v[32:35], s[18:19]
	global_store_dwordx4 v171, v[28:31], s[78:79]
	global_store_dwordx4 v171, v[24:27], s[22:23]
	s_waitcnt vmcnt(12)
	s_mov_b64 vcc, s[6:7]
	v_cndmask_b32_dpp v0, v234, v204, vcc row_ror:8 row_mask:0xf bank_mask:0xf
	v_cndmask_b32_dpp v1, v235, v205, vcc row_ror:8 row_mask:0xf bank_mask:0xf
	v_cndmask_b32_dpp v2, v236, v206, vcc row_ror:8 row_mask:0xf bank_mask:0xf
	v_cndmask_b32_dpp v3, v237, v207, vcc row_ror:8 row_mask:0xf bank_mask:0xf
	s_not_b64 vcc, s[6:7]
	v_cndmask_b32_dpp v4, v204, v234, vcc row_ror:8 row_mask:0xf bank_mask:0xf
	v_cndmask_b32_dpp v5, v205, v235, vcc row_ror:8 row_mask:0xf bank_mask:0xf
	v_cndmask_b32_dpp v6, v206, v236, vcc row_ror:8 row_mask:0xf bank_mask:0xf
	v_cndmask_b32_dpp v7, v207, v237, vcc row_ror:8 row_mask:0xf bank_mask:0xf
	v_lshlrev_b32_e32 v246, 16, v0
	v_and_b32_e32 v247, 0xffff0000, v0
	v_pk_fma_f32 v[20:21], v[20:21], v[142:143], v[246:247]
	v_lshlrev_b32_e32 v248, 16, v1
	v_and_b32_e32 v249, 0xffff0000, v1
	v_pk_fma_f32 v[22:23], v[22:23], v[144:145], v[248:249]
	v_lshlrev_b32_e32 v250, 16, v2
	v_and_b32_e32 v251, 0xffff0000, v2
	v_pk_fma_f32 v[16:17], v[16:17], v[150:151], v[250:251]
	v_lshlrev_b32_e32 v208, 16, v3
	v_and_b32_e32 v209, 0xffff0000, v3
	v_pk_fma_f32 v[18:19], v[18:19], v[152:153], v[208:209]
	v_lshlrev_b32_e32 v246, 16, v4
	v_and_b32_e32 v247, 0xffff0000, v4
	v_pk_fma_f32 v[12:13], v[12:13], v[138:139], v[246:247]
	v_lshlrev_b32_e32 v248, 16, v5
	v_and_b32_e32 v249, 0xffff0000, v5
	v_pk_fma_f32 v[14:15], v[14:15], v[140:141], v[248:249]
	v_lshlrev_b32_e32 v250, 16, v6
	v_and_b32_e32 v251, 0xffff0000, v6
	v_pk_fma_f32 v[8:9], v[8:9], v[146:147], v[250:251]
	v_lshlrev_b32_e32 v208, 16, v7
	v_and_b32_e32 v209, 0xffff0000, v7
	v_pk_fma_f32 v[10:11], v[10:11], v[148:149], v[208:209]
	v_cvt_pk_bf16_f32 v0, v20, v21
	v_cvt_pk_bf16_f32 v1, v22, v23
	v_cvt_pk_bf16_f32 v2, v16, v17
	v_cvt_pk_bf16_f32 v3, v18, v19
	v_cvt_pk_bf16_f32 v4, v12, v13
	v_cvt_pk_bf16_f32 v5, v14, v15
	v_cvt_pk_bf16_f32 v6, v8, v9
	v_cvt_pk_bf16_f32 v7, v10, v11
	v_mul_f32_e32 v246, v21, v21
	v_mul_f32_e32 v248, v23, v23
	v_fmac_f32_e32 v246, v20, v20
	v_fmac_f32_e32 v248, v22, v22
	v_add_f32_e32 v246, v246, v248
	v_mul_f32_e32 v248, v17, v17
	v_fmac_f32_e32 v248, v16, v16
	v_add_f32_e32 v246, v246, v248
	v_mul_f32_e32 v248, v19, v19
	v_fmac_f32_e32 v248, v18, v18
	v_add_f32_e32 v246, v248, v246
	v_mul_f32_e32 v247, v13, v13
	v_mul_f32_e32 v248, v15, v15
	v_fmac_f32_e32 v247, v12, v12
	v_fmac_f32_e32 v248, v14, v14
	v_add_f32_e32 v247, v247, v248
	v_mul_f32_e32 v248, v9, v9
	v_fmac_f32_e32 v248, v8, v8
	v_add_f32_e32 v247, v247, v248
	v_mul_f32_e32 v248, v11, v11
	v_fmac_f32_e32 v248, v10, v10
	v_add_f32_e32 v247, v248, v247
	v_add_f32_e32 v246, v246, v247
	v_mov_b32_e32 v247, v246
	s_nop 1
	v_permlane16_swap_b32_e32 v246, v247
	s_nop 1
	v_add_f32_e32 v246, v246, v247
	v_mov_b32_e32 v247, v246
	s_nop 1
	v_permlane32_swap_b32_e32 v246, v247
	v_add_u32_e32 v248, s8, v223
	s_nop 0
	v_add_f32_e32 v246, v246, v247
	s_mov_b64 exec, s[44:45]
	ds_write_b32 v248, v246 offset:2816
	s_mov_b64 exec, -1
	v_pk_mul_f32 v[20:21], v[180:181], v[20:21]
	v_pk_mul_f32 v[22:23], v[182:183], v[22:23]
	v_pk_mul_f32 v[16:17], v[184:185], v[16:17]
	v_pk_mul_f32 v[18:19], v[186:187], v[18:19]
	v_pk_mul_f32 v[12:13], v[188:189], v[12:13]
	v_pk_mul_f32 v[14:15], v[190:191], v[14:15]
	v_pk_mul_f32 v[8:9], v[192:193], v[8:9]
	v_pk_mul_f32 v[10:11], v[194:195], v[10:11]
	v_cvt_pk_bf16_f32 v246, v20, v21
	v_cvt_pk_bf16_f32 v247, v22, v23
	v_cvt_pk_bf16_f32 v248, v16, v17
	v_cvt_pk_bf16_f32 v249, v18, v19
	v_cvt_pk_bf16_f32 v250, v12, v13
	v_cvt_pk_bf16_f32 v251, v14, v15
	v_cvt_pk_bf16_f32 v208, v8, v9
	v_cvt_pk_bf16_f32 v209, v10, v11
	s_add_u32 s2, s2, 0x8000
	s_addc_u32 s3, s3, 0
	s_add_u32 s18, s18, 0x8000
	s_addc_u32 s19, s19, 0
	s_add_u32 s78, s78, 0x8000
	s_addc_u32 s79, s79, 0
	s_add_u32 s22, s22, 0x8000
	s_addc_u32 s23, s23, 0
	s_mov_b64 vcc, s[6:7]
	v_cndmask_b32_dpp v20, v4, v0, vcc row_ror:8 row_mask:0xf bank_mask:0xf
	v_cndmask_b32_dpp v21, v5, v1, vcc row_ror:8 row_mask:0xf bank_mask:0xf
	v_cndmask_b32_dpp v22, v6, v2, vcc row_ror:8 row_mask:0xf bank_mask:0xf
	v_cndmask_b32_dpp v23, v7, v3, vcc row_ror:8 row_mask:0xf bank_mask:0xf
	v_cndmask_b32_dpp v12, v250, v246, vcc row_ror:8 row_mask:0xf bank_mask:0xf
	v_cndmask_b32_dpp v13, v251, v247, vcc row_ror:8 row_mask:0xf bank_mask:0xf
	v_cndmask_b32_dpp v14, v208, v248, vcc row_ror:8 row_mask:0xf bank_mask:0xf
	v_cndmask_b32_dpp v15, v209, v249, vcc row_ror:8 row_mask:0xf bank_mask:0xf
	s_not_b64 vcc, s[6:7]
	v_cndmask_b32_dpp v16, v0, v4, vcc row_ror:8 row_mask:0xf bank_mask:0xf
	v_cndmask_b32_dpp v17, v1, v5, vcc row_ror:8 row_mask:0xf bank_mask:0xf
	v_cndmask_b32_dpp v18, v2, v6, vcc row_ror:8 row_mask:0xf bank_mask:0xf
	v_cndmask_b32_dpp v19, v3, v7, vcc row_ror:8 row_mask:0xf bank_mask:0xf
	v_cndmask_b32_dpp v8, v246, v250, vcc row_ror:8 row_mask:0xf bank_mask:0xf
	v_cndmask_b32_dpp v9, v247, v251, vcc row_ror:8 row_mask:0xf bank_mask:0xf
	v_cndmask_b32_dpp v10, v248, v208, vcc row_ror:8 row_mask:0xf bank_mask:0xf
	v_cndmask_b32_dpp v11, v249, v209, vcc row_ror:8 row_mask:0xf bank_mask:0xf
	global_store_dwordx4 v171, v[20:23], s[2:3]
	global_store_dwordx4 v171, v[16:19], s[18:19]
	global_store_dwordx4 v171, v[12:15], s[78:79]
	global_store_dwordx4 v171, v[8:11], s[22:23]
	s_mov_b32 s100, 1
	s_branch .LBB0_714

.Lfo_first:
	s_lshr_b32 s14, s34, 3
	s_mul_i32 s14, s14, 0x3000
	s_add_u32 s16, s86, s14
	s_addc_u32 s17, s87, 0
	s_add_u32 s16, s16, 0x2000
	s_addc_u32 s17, s17, 0
	s_add_u32 s86, s88, s14
	s_addc_u32 s87, s89, 0
	s_add_u32 s86, s86, 0x1000
	s_addc_u32 s87, s87, 0
	v_lshl_add_u32 v171, v170, 1, v96
	v_lshl_add_u32 v171, v222, 11, v171
	v_lshlrev_b32_e32 v170, 2, v170
	s_lshl_b32 s14, s34, 8
	s_add_i32 s14, s14, s81
	s_mov_b64 s[12:13], s[18:19]
	s_lshl_b32 s31, s14, 12
	s_lshl_b32 s14, s14, 11
	s_add_u32 s2, s2, s14
	s_addc_u32 s3, s3, 0
	s_add_u32 s78, s78, s14
	s_addc_u32 s79, s79, 0
	s_add_u32 s22, s78, 0x4000
	s_addc_u32 s23, s79, 0
	s_add_u32 s18, s2, 0x4000
	s_addc_u32 s19, s3, 0
	s_add_u32 s14, s12, s31
	s_addc_u32 s15, s13, 0
	global_load_dwordx4 v[142:145], v170, s[16:17]
	global_load_dwordx4 v[150:153], v170, s[16:17] offset:16
	global_load_dwordx4 v[138:141], v170, s[16:17] offset:128
	global_load_dwordx4 v[146:149], v170, s[16:17] offset:144
	v_lshl_add_u32 v96, v163, 12, v170
	global_load_dwordx4 v[196:199], v96, s[14:15]
	global_load_dwordx4 v[200:203], v96, s[14:15] offset:16
	global_load_dwordx4 v[204:207], v96, s[14:15] offset:128
	global_load_dwordx4 v[234:237], v96, s[14:15] offset:144
	global_load_dwordx4 v[180:183], v170, s[86:87]
	global_load_dwordx4 v[184:187], v170, s[86:87] offset:16
	global_load_dwordx4 v[188:191], v170, s[86:87] offset:128
	global_load_dwordx4 v[192:195], v170, s[86:87] offset:144
	global_load_dwordx4 v[238:241], v170, s[26:27]
	global_load_dwordx4 v[242:245], v170, s[26:27] offset:16
	global_load_dwordx4 v[246:249], v170, s[26:27] offset:128
	global_load_dwordx4 v[4:7], v170, s[26:27] offset:144
	s_waitcnt vmcnt(0)
	v_pk_add_f32 v[182:183], v[182:183], 1.0 op_sel_hi:[1,0]
	v_pk_add_f32 v[180:181], v[180:181], 1.0 op_sel_hi:[1,0]
	v_pk_add_f32 v[186:187], v[186:187], 1.0 op_sel_hi:[1,0]
	v_pk_add_f32 v[184:185], v[184:185], 1.0 op_sel_hi:[1,0]
	v_pk_add_f32 v[190:191], v[190:191], 1.0 op_sel_hi:[1,0]
	v_pk_add_f32 v[188:189], v[188:189], 1.0 op_sel_hi:[1,0]
	v_pk_add_f32 v[194:195], v[194:195], 1.0 op_sel_hi:[1,0]
	v_pk_add_f32 v[192:193], v[192:193], 1.0 op_sel_hi:[1,0]
	v_pk_mul_f32 v[182:183], v[240:241], v[182:183]
	v_pk_mul_f32 v[180:181], v[238:239], v[180:181]
	v_pk_mul_f32 v[186:187], v[244:245], v[186:187]
	v_pk_mul_f32 v[184:185], v[242:243], v[184:185]
	v_pk_mul_f32 v[190:191], v[248:249], v[190:191]
	v_pk_mul_f32 v[188:189], v[246:247], v[188:189]
	v_pk_mul_f32 v[194:195], v[6:7], v[194:195]
	v_pk_mul_f32 v[192:193], v[4:5], v[192:193]
	s_add_u32 s14, s14, 0x10000
	s_addc_u32 s15, s15, 0
	global_load_dwordx4 v[238:241], v96, s[14:15]
	global_load_dwordx4 v[242:245], v96, s[14:15] offset:16
	v_pk_fma_f32 v[134:135], v[134:135], v[142:143], v[196:197]
	v_pk_fma_f32 v[136:137], v[136:137], v[144:145], v[198:199]
	v_pk_fma_f32 v[130:131], v[130:131], v[150:151], v[200:201]
	v_pk_fma_f32 v[132:133], v[132:133], v[152:153], v[202:203]
	v_pk_fma_f32 v[126:127], v[126:127], v[138:139], v[204:205]
	v_pk_fma_f32 v[128:129], v[128:129], v[140:141], v[206:207]
	v_pk_fma_f32 v[122:123], v[122:123], v[146:147], v[234:235]
	v_pk_fma_f32 v[124:125], v[124:125], v[148:149], v[236:237]
	global_load_dwordx4 v[196:199], v96, s[14:15] offset:128
	global_load_dwordx4 v[200:203], v96, s[14:15] offset:144
	s_add_u32 s14, s14, 0x10000
	s_addc_u32 s15, s15, 0
	global_load_dwordx4 v[204:207], v96, s[14:15]
	global_load_dwordx4 v[234:237], v96, s[14:15] offset:16
	v_cvt_pk_bf16_f32 v0, v134, v135
	v_cvt_pk_bf16_f32 v1, v136, v137
	v_cvt_pk_bf16_f32 v2, v130, v131
	v_cvt_pk_bf16_f32 v3, v132, v133
	v_cvt_pk_bf16_f32 v4, v126, v127
	v_cvt_pk_bf16_f32 v5, v128, v129
	v_cvt_pk_bf16_f32 v6, v122, v123
	v_cvt_pk_bf16_f32 v7, v124, v125
	v_mul_f32_e32 v246, v135, v135
	v_mul_f32_e32 v248, v137, v137
	v_fmac_f32_e32 v246, v134, v134
	v_fmac_f32_e32 v248, v136, v136
	v_add_f32_e32 v246, v246, v248
	v_mul_f32_e32 v248, v131, v131
	v_fmac_f32_e32 v248, v130, v130
	v_add_f32_e32 v246, v246, v248
	v_mul_f32_e32 v248, v133, v133
	v_fmac_f32_e32 v248, v132, v132
	v_add_f32_e32 v246, v248, v246
	v_mul_f32_e32 v247, v127, v127
	v_mul_f32_e32 v248, v129, v129
	v_fmac_f32_e32 v247, v126, v126
	v_fmac_f32_e32 v248, v128, v128
	v_add_f32_e32 v247, v247, v248
	v_mul_f32_e32 v248, v123, v123
	v_fmac_f32_e32 v248, v122, v122
	v_add_f32_e32 v247, v247, v248
	v_mul_f32_e32 v248, v125, v125
	v_fmac_f32_e32 v248, v124, v124
	v_add_f32_e32 v247, v248, v247
	v_add_f32_e32 v246, v246, v247
	v_mov_b32_e32 v247, v246
	s_nop 1
	v_permlane16_swap_b32_e32 v246, v247
	s_nop 1
	v_add_f32_e32 v246, v246, v247
	v_mov_b32_e32 v247, v246
	s_nop 1
	v_permlane32_swap_b32_e32 v246, v247
	v_add_u32_e32 v248, s8, v223
	s_nop 0
	v_add_f32_e32 v246, v246, v247
	s_mov_b64 exec, s[44:45]
	ds_write_b32 v248, v246
	s_mov_b64 exec, -1
	v_pk_mul_f32 v[134:135], v[180:181], v[134:135]
	v_pk_mul_f32 v[136:137], v[182:183], v[136:137]
	v_pk_mul_f32 v[130:131], v[184:185], v[130:131]
	v_pk_mul_f32 v[132:133], v[186:187], v[132:133]
	v_pk_mul_f32 v[126:127], v[188:189], v[126:127]
	v_pk_mul_f32 v[128:129], v[190:191], v[128:129]
	v_pk_mul_f32 v[122:123], v[192:193], v[122:123]
	v_pk_mul_f32 v[124:125], v[194:195], v[124:125]
	v_cvt_pk_bf16_f32 v246, v134, v135
	v_cvt_pk_bf16_f32 v247, v136, v137
	v_cvt_pk_bf16_f32 v248, v130, v131
	v_cvt_pk_bf16_f32 v249, v132, v133
	v_cvt_pk_bf16_f32 v250, v126, v127
	v_cvt_pk_bf16_f32 v251, v128, v129
	v_cvt_pk_bf16_f32 v208, v122, v123
	v_cvt_pk_bf16_f32 v209, v124, v125
	s_nop 1
	s_mov_b64 vcc, s[6:7]
	v_cndmask_b32_dpp v134, v4, v0, vcc row_ror:8 row_mask:0xf bank_mask:0xf
	v_cndmask_b32_dpp v135, v5, v1, vcc row_ror:8 row_mask:0xf bank_mask:0xf
	v_cndmask_b32_dpp v136, v6, v2, vcc row_ror:8 row_mask:0xf bank_mask:0xf
	v_cndmask_b32_dpp v137, v7, v3, vcc row_ror:8 row_mask:0xf bank_mask:0xf
	v_cndmask_b32_dpp v126, v250, v246, vcc row_ror:8 row_mask:0xf bank_mask:0xf
	v_cndmask_b32_dpp v127, v251, v247, vcc row_ror:8 row_mask:0xf bank_mask:0xf
	v_cndmask_b32_dpp v128, v208, v248, vcc row_ror:8 row_mask:0xf bank_mask:0xf
	v_cndmask_b32_dpp v129, v209, v249, vcc row_ror:8 row_mask:0xf bank_mask:0xf
	s_not_b64 vcc, s[6:7]
	v_cndmask_b32_dpp v130, v0, v4, vcc row_ror:8 row_mask:0xf bank_mask:0xf
	v_cndmask_b32_dpp v131, v1, v5, vcc row_ror:8 row_mask:0xf bank_mask:0xf
	v_cndmask_b32_dpp v132, v2, v6, vcc row_ror:8 row_mask:0xf bank_mask:0xf
	v_cndmask_b32_dpp v133, v3, v7, vcc row_ror:8 row_mask:0xf bank_mask:0xf
	v_cndmask_b32_dpp v122, v246, v250, vcc row_ror:8 row_mask:0xf bank_mask:0xf
	v_cndmask_b32_dpp v123, v247, v251, vcc row_ror:8 row_mask:0xf bank_mask:0xf
	v_cndmask_b32_dpp v124, v248, v208, vcc row_ror:8 row_mask:0xf bank_mask:0xf
	v_cndmask_b32_dpp v125, v249, v209, vcc row_ror:8 row_mask:0xf bank_mask:0xf
	global_store_dwordx4 v171, v[134:137], s[2:3]
	global_store_dwordx4 v171, v[130:133], s[18:19]
	global_store_dwordx4 v171, v[126:129], s[78:79]
	global_store_dwordx4 v171, v[122:125], s[22:23]
	s_waitcnt vmcnt(6)
	v_pk_fma_f32 v[118:119], v[118:119], v[142:143], v[238:239]
	v_pk_fma_f32 v[120:121], v[120:121], v[144:145], v[240:241]
	v_pk_fma_f32 v[114:115], v[114:115], v[150:151], v[242:243]
	v_pk_fma_f32 v[116:117], v[116:117], v[152:153], v[244:245]
	v_pk_fma_f32 v[110:111], v[110:111], v[138:139], v[196:197]
	v_pk_fma_f32 v[112:113], v[112:113], v[140:141], v[198:199]
	v_pk_fma_f32 v[106:107], v[106:107], v[146:147], v[200:201]
	v_pk_fma_f32 v[108:109], v[108:109], v[148:149], v[202:203]
	global_load_dwordx4 v[238:241], v96, s[14:15] offset:128
	global_load_dwordx4 v[242:245], v96, s[14:15] offset:144
	s_add_u32 s14, s14, 0x10000
	s_addc_u32 s15, s15, 0
	global_load_dwordx4 v[196:199], v96, s[14:15]
	global_load_dwordx4 v[200:203], v96, s[14:15] offset:16
	v_cvt_pk_bf16_f32 v0, v118, v119
	v_cvt_pk_bf16_f32 v1, v120, v121
	v_cvt_pk_bf16_f32 v2, v114, v115
	v_cvt_pk_bf16_f32 v3, v116, v117
	v_cvt_pk_bf16_f32 v4, v110, v111
	v_cvt_pk_bf16_f32 v5, v112, v113
	v_cvt_pk_bf16_f32 v6, v106, v107
	v_cvt_pk_bf16_f32 v7, v108, v109
	v_mul_f32_e32 v246, v119, v119
	v_mul_f32_e32 v248, v121, v121
	v_fmac_f32_e32 v246, v118, v118
	v_fmac_f32_e32 v248, v120, v120
	v_add_f32_e32 v246, v246, v248
	v_mul_f32_e32 v248, v115, v115
	v_fmac_f32_e32 v248, v114, v114
	v_add_f32_e32 v246, v246, v248
	v_mul_f32_e32 v248, v117, v117
	v_fmac_f32_e32 v248, v116, v116
	v_add_f32_e32 v246, v248, v246
	v_mul_f32_e32 v247, v111, v111
	v_mul_f32_e32 v248, v113, v113
	v_fmac_f32_e32 v247, v110, v110
	v_fmac_f32_e32 v248, v112, v112
	v_add_f32_e32 v247, v247, v248
	v_mul_f32_e32 v248, v107, v107
	v_fmac_f32_e32 v248, v106, v106
	v_add_f32_e32 v247, v247, v248
	v_mul_f32_e32 v248, v109, v109
	v_fmac_f32_e32 v248, v108, v108
	v_add_f32_e32 v247, v248, v247
	v_add_f32_e32 v246, v246, v247
	v_mov_b32_e32 v247, v246
	s_nop 1
	v_permlane16_swap_b32_e32 v246, v247
	s_nop 1
	v_add_f32_e32 v246, v246, v247
	v_mov_b32_e32 v247, v246
	s_nop 1
	v_permlane32_swap_b32_e32 v246, v247
	v_add_u32_e32 v248, s8, v223
	s_nop 0
	v_add_f32_e32 v246, v246, v247
	s_mov_b64 exec, s[44:45]
	ds_write_b32 v248, v246 offset:256
	s_mov_b64 exec, -1
	v_pk_mul_f32 v[118:119], v[180:181], v[118:119]
	v_pk_mul_f32 v[120:121], v[182:183], v[120:121]
	v_pk_mul_f32 v[114:115], v[184:185], v[114:115]
	v_pk_mul_f32 v[116:117], v[186:187], v[116:117]
	v_pk_mul_f32 v[110:111], v[188:189], v[110:111]
	v_pk_mul_f32 v[112:113], v[190:191], v[112:113]
	v_pk_mul_f32 v[106:107], v[192:193], v[106:107]
	v_pk_mul_f32 v[108:109], v[194:195], v[108:109]
	v_cvt_pk_bf16_f32 v246, v118, v119
	v_cvt_pk_bf16_f32 v247, v120, v121
	v_cvt_pk_bf16_f32 v248, v114, v115
	v_cvt_pk_bf16_f32 v249, v116, v117
	v_cvt_pk_bf16_f32 v250, v110, v111
	v_cvt_pk_bf16_f32 v251, v112, v113
	v_cvt_pk_bf16_f32 v208, v106, v107
	v_cvt_pk_bf16_f32 v209, v108, v109
	s_add_u32 s2, s2, 0x8000
	s_addc_u32 s3, s3, 0
	s_add_u32 s18, s18, 0x8000
	s_addc_u32 s19, s19, 0
	s_add_u32 s78, s78, 0x8000
	s_addc_u32 s79, s79, 0
	s_add_u32 s22, s22, 0x8000
	s_addc_u32 s23, s23, 0
	s_mov_b64 vcc, s[6:7]
	v_cndmask_b32_dpp v118, v4, v0, vcc row_ror:8 row_mask:0xf bank_mask:0xf
	v_cndmask_b32_dpp v119, v5, v1, vcc row_ror:8 row_mask:0xf bank_mask:0xf
	v_cndmask_b32_dpp v120, v6, v2, vcc row_ror:8 row_mask:0xf bank_mask:0xf
	v_cndmask_b32_dpp v121, v7, v3, vcc row_ror:8 row_mask:0xf bank_mask:0xf
	v_cndmask_b32_dpp v110, v250, v246, vcc row_ror:8 row_mask:0xf bank_mask:0xf
	v_cndmask_b32_dpp v111, v251, v247, vcc row_ror:8 row_mask:0xf bank_mask:0xf
	v_cndmask_b32_dpp v112, v208, v248, vcc row_ror:8 row_mask:0xf bank_mask:0xf
	v_cndmask_b32_dpp v113, v209, v249, vcc row_ror:8 row_mask:0xf bank_mask:0xf
	s_not_b64 vcc, s[6:7]
	v_cndmask_b32_dpp v114, v0, v4, vcc row_ror:8 row_mask:0xf bank_mask:0xf
	v_cndmask_b32_dpp v115, v1, v5, vcc row_ror:8 row_mask:0xf bank_mask:0xf
	v_cndmask_b32_dpp v116, v2, v6, vcc row_ror:8 row_mask:0xf bank_mask:0xf
	v_cndmask_b32_dpp v117, v3, v7, vcc row_ror:8 row_mask:0xf bank_mask:0xf
	v_cndmask_b32_dpp v106, v246, v250, vcc row_ror:8 row_mask:0xf bank_mask:0xf
	v_cndmask_b32_dpp v107, v247, v251, vcc row_ror:8 row_mask:0xf bank_mask:0xf
	v_cndmask_b32_dpp v108, v248, v208, vcc row_ror:8 row_mask:0xf bank_mask:0xf
	v_cndmask_b32_dpp v109, v249, v209, vcc row_ror:8 row_mask:0xf bank_mask:0xf
	global_store_dwordx4 v171, v[118:121], s[2:3]
	global_store_dwordx4 v171, v[114:117], s[18:19]
	global_store_dwordx4 v171, v[110:113], s[78:79]
	global_store_dwordx4 v171, v[106:109], s[22:23]
	s_waitcnt vmcnt(6)
	v_pk_fma_f32 v[102:103], v[102:103], v[142:143], v[204:205]
	v_pk_fma_f32 v[104:105], v[104:105], v[144:145], v[206:207]
	v_pk_fma_f32 v[98:99], v[98:99], v[150:151], v[234:235]
	v_pk_fma_f32 v[100:101], v[100:101], v[152:153], v[236:237]
	v_pk_fma_f32 v[92:93], v[92:93], v[138:139], v[238:239]
	v_pk_fma_f32 v[94:95], v[94:95], v[140:141], v[240:241]
	v_pk_fma_f32 v[88:89], v[88:89], v[146:147], v[242:243]
	v_pk_fma_f32 v[90:91], v[90:91], v[148:149], v[244:245]
	global_load_dwordx4 v[204:207], v96, s[14:15] offset:128
	global_load_dwordx4 v[234:237], v96, s[14:15] offset:144
	s_add_u32 s14, s14, 0x50000
	s_addc_u32 s15, s15, 0
	global_load_dwordx4 v[238:241], v96, s[14:15]
	global_load_dwordx4 v[242:245], v96, s[14:15] offset:16
	v_cvt_pk_bf16_f32 v0, v102, v103
	v_cvt_pk_bf16_f32 v1, v104, v105
	v_cvt_pk_bf16_f32 v2, v98, v99
	v_cvt_pk_bf16_f32 v3, v100, v101
	v_cvt_pk_bf16_f32 v4, v92, v93
	v_cvt_pk_bf16_f32 v5, v94, v95
	v_cvt_pk_bf16_f32 v6, v88, v89
	v_cvt_pk_bf16_f32 v7, v90, v91
	v_mul_f32_e32 v246, v103, v103
	v_mul_f32_e32 v248, v105, v105
	v_fmac_f32_e32 v246, v102, v102
	v_fmac_f32_e32 v248, v104, v104
	v_add_f32_e32 v246, v246, v248
	v_mul_f32_e32 v248, v99, v99
	v_fmac_f32_e32 v248, v98, v98
	v_add_f32_e32 v246, v246, v248
	v_mul_f32_e32 v248, v101, v101
	v_fmac_f32_e32 v248, v100, v100
	v_add_f32_e32 v246, v248, v246
	v_mul_f32_e32 v247, v93, v93
	v_mul_f32_e32 v248, v95, v95
	v_fmac_f32_e32 v247, v92, v92
	v_fmac_f32_e32 v248, v94, v94
	v_add_f32_e32 v247, v247, v248
	v_mul_f32_e32 v248, v89, v89
	v_fmac_f32_e32 v248, v88, v88
	v_add_f32_e32 v247, v247, v248
	v_mul_f32_e32 v248, v91, v91
	v_fmac_f32_e32 v248, v90, v90
	v_add_f32_e32 v247, v248, v247
	v_add_f32_e32 v246, v246, v247
	v_mov_b32_e32 v247, v246
	s_nop 1
	v_permlane16_swap_b32_e32 v246, v247
	s_nop 1
	v_add_f32_e32 v246, v246, v247
	v_mov_b32_e32 v247, v246
	s_nop 1
	v_permlane32_swap_b32_e32 v246, v247
	v_add_u32_e32 v248, s8, v223
	s_nop 0
	v_add_f32_e32 v246, v246, v247
	s_mov_b64 exec, s[44:45]
	ds_write_b32 v248, v246 offset:512
	s_mov_b64 exec, -1
	v_pk_mul_f32 v[102:103], v[180:181], v[102:103]
	v_pk_mul_f32 v[104:105], v[182:183], v[104:105]
	v_pk_mul_f32 v[98:99], v[184:185], v[98:99]
	v_pk_mul_f32 v[100:101], v[186:187], v[100:101]
	v_pk_mul_f32 v[92:93], v[188:189], v[92:93]
	v_pk_mul_f32 v[94:95], v[190:191], v[94:95]
	v_pk_mul_f32 v[88:89], v[192:193], v[88:89]
	v_pk_mul_f32 v[90:91], v[194:195], v[90:91]
	v_cvt_pk_bf16_f32 v246, v102, v103
	v_cvt_pk_bf16_f32 v247, v104, v105
	v_cvt_pk_bf16_f32 v248, v98, v99
	v_cvt_pk_bf16_f32 v249, v100, v101
	v_cvt_pk_bf16_f32 v250, v92, v93
	v_cvt_pk_bf16_f32 v251, v94, v95
	v_cvt_pk_bf16_f32 v208, v88, v89
	v_cvt_pk_bf16_f32 v209, v90, v91
	s_add_u32 s2, s2, 0x8000
	s_addc_u32 s3, s3, 0
	s_add_u32 s18, s18, 0x8000
	s_addc_u32 s19, s19, 0
	s_add_u32 s78, s78, 0x8000
	s_addc_u32 s79, s79, 0
	s_add_u32 s22, s22, 0x8000
	s_addc_u32 s23, s23, 0
	s_mov_b64 vcc, s[6:7]
	v_cndmask_b32_dpp v102, v4, v0, vcc row_ror:8 row_mask:0xf bank_mask:0xf
	v_cndmask_b32_dpp v103, v5, v1, vcc row_ror:8 row_mask:0xf bank_mask:0xf
	v_cndmask_b32_dpp v104, v6, v2, vcc row_ror:8 row_mask:0xf bank_mask:0xf
	v_cndmask_b32_dpp v105, v7, v3, vcc row_ror:8 row_mask:0xf bank_mask:0xf
	v_cndmask_b32_dpp v92, v250, v246, vcc row_ror:8 row_mask:0xf bank_mask:0xf
	v_cndmask_b32_dpp v93, v251, v247, vcc row_ror:8 row_mask:0xf bank_mask:0xf
	v_cndmask_b32_dpp v94, v208, v248, vcc row_ror:8 row_mask:0xf bank_mask:0xf
	v_cndmask_b32_dpp v95, v209, v249, vcc row_ror:8 row_mask:0xf bank_mask:0xf
	s_not_b64 vcc, s[6:7]
	v_cndmask_b32_dpp v98, v0, v4, vcc row_ror:8 row_mask:0xf bank_mask:0xf
	v_cndmask_b32_dpp v99, v1, v5, vcc row_ror:8 row_mask:0xf bank_mask:0xf
	v_cndmask_b32_dpp v100, v2, v6, vcc row_ror:8 row_mask:0xf bank_mask:0xf
	v_cndmask_b32_dpp v101, v3, v7, vcc row_ror:8 row_mask:0xf bank_mask:0xf
	v_cndmask_b32_dpp v88, v246, v250, vcc row_ror:8 row_mask:0xf bank_mask:0xf
	v_cndmask_b32_dpp v89, v247, v251, vcc row_ror:8 row_mask:0xf bank_mask:0xf
	v_cndmask_b32_dpp v90, v248, v208, vcc row_ror:8 row_mask:0xf bank_mask:0xf
	v_cndmask_b32_dpp v91, v249, v209, vcc row_ror:8 row_mask:0xf bank_mask:0xf
	global_store_dwordx4 v171, v[102:105], s[2:3]
	global_store_dwordx4 v171, v[98:101], s[18:19]
	global_store_dwordx4 v171, v[92:95], s[78:79]
	global_store_dwordx4 v171, v[88:91], s[22:23]
	s_waitcnt vmcnt(6)
	v_pk_fma_f32 v[84:85], v[84:85], v[142:143], v[196:197]
	v_pk_fma_f32 v[86:87], v[86:87], v[144:145], v[198:199]
	v_pk_fma_f32 v[80:81], v[80:81], v[150:151], v[200:201]
	v_pk_fma_f32 v[82:83], v[82:83], v[152:153], v[202:203]
	v_pk_fma_f32 v[76:77], v[76:77], v[138:139], v[204:205]
	v_pk_fma_f32 v[78:79], v[78:79], v[140:141], v[206:207]
	v_pk_fma_f32 v[72:73], v[72:73], v[146:147], v[234:235]
	v_pk_fma_f32 v[74:75], v[74:75], v[148:149], v[236:237]
	global_load_dwordx4 v[196:199], v96, s[14:15] offset:128
	global_load_dwordx4 v[200:203], v96, s[14:15] offset:144
	s_add_u32 s14, s14, 0x10000
	s_addc_u32 s15, s15, 0
	global_load_dwordx4 v[204:207], v96, s[14:15]
	global_load_dwordx4 v[234:237], v96, s[14:15] offset:16
	v_cvt_pk_bf16_f32 v0, v84, v85
	v_cvt_pk_bf16_f32 v1, v86, v87
	v_cvt_pk_bf16_f32 v2, v80, v81
	v_cvt_pk_bf16_f32 v3, v82, v83
	v_cvt_pk_bf16_f32 v4, v76, v77
	v_cvt_pk_bf16_f32 v5, v78, v79
	v_cvt_pk_bf16_f32 v6, v72, v73
	v_cvt_pk_bf16_f32 v7, v74, v75
	v_mul_f32_e32 v246, v85, v85
	v_mul_f32_e32 v248, v87, v87
	v_fmac_f32_e32 v246, v84, v84
	v_fmac_f32_e32 v248, v86, v86
	v_add_f32_e32 v246, v246, v248
	v_mul_f32_e32 v248, v81, v81
	v_fmac_f32_e32 v248, v80, v80
	v_add_f32_e32 v246, v246, v248
	v_mul_f32_e32 v248, v83, v83
	v_fmac_f32_e32 v248, v82, v82
	v_add_f32_e32 v246, v248, v246
	v_mul_f32_e32 v247, v77, v77
	v_mul_f32_e32 v248, v79, v79
	v_fmac_f32_e32 v247, v76, v76
	v_fmac_f32_e32 v248, v78, v78
	v_add_f32_e32 v247, v247, v248
	v_mul_f32_e32 v248, v73, v73
	v_fmac_f32_e32 v248, v72, v72
	v_add_f32_e32 v247, v247, v248
	v_mul_f32_e32 v248, v75, v75
	v_fmac_f32_e32 v248, v74, v74
	v_add_f32_e32 v247, v248, v247
	v_add_f32_e32 v246, v246, v247
	v_mov_b32_e32 v247, v246
	s_nop 1
	v_permlane16_swap_b32_e32 v246, v247
	s_nop 1
	v_add_f32_e32 v246, v246, v247
	v_mov_b32_e32 v247, v246
	s_nop 1
	v_permlane32_swap_b32_e32 v246, v247
	v_add_u32_e32 v248, s8, v223
	s_nop 0
	v_add_f32_e32 v246, v246, v247
	s_mov_b64 exec, s[44:45]
	ds_write_b32 v248, v246 offset:768
	s_mov_b64 exec, -1
	v_pk_mul_f32 v[84:85], v[180:181], v[84:85]
	v_pk_mul_f32 v[86:87], v[182:183], v[86:87]
	v_pk_mul_f32 v[80:81], v[184:185], v[80:81]
	v_pk_mul_f32 v[82:83], v[186:187], v[82:83]
	v_pk_mul_f32 v[76:77], v[188:189], v[76:77]
	v_pk_mul_f32 v[78:79], v[190:191], v[78:79]
	v_pk_mul_f32 v[72:73], v[192:193], v[72:73]
	v_pk_mul_f32 v[74:75], v[194:195], v[74:75]
	v_cvt_pk_bf16_f32 v246, v84, v85
	v_cvt_pk_bf16_f32 v247, v86, v87
	v_cvt_pk_bf16_f32 v248, v80, v81
	v_cvt_pk_bf16_f32 v249, v82, v83
	v_cvt_pk_bf16_f32 v250, v76, v77
	v_cvt_pk_bf16_f32 v251, v78, v79
	v_cvt_pk_bf16_f32 v208, v72, v73
	v_cvt_pk_bf16_f32 v209, v74, v75
	s_add_u32 s2, s2, 0x8000
	s_addc_u32 s3, s3, 0
	s_add_u32 s18, s18, 0x8000
	s_addc_u32 s19, s19, 0
	s_add_u32 s78, s78, 0x8000
	s_addc_u32 s79, s79, 0
	s_add_u32 s22, s22, 0x8000
	s_addc_u32 s23, s23, 0
	s_mov_b64 vcc, s[6:7]
	v_cndmask_b32_dpp v84, v4, v0, vcc row_ror:8 row_mask:0xf bank_mask:0xf
	v_cndmask_b32_dpp v85, v5, v1, vcc row_ror:8 row_mask:0xf bank_mask:0xf
	v_cndmask_b32_dpp v86, v6, v2, vcc row_ror:8 row_mask:0xf bank_mask:0xf
	v_cndmask_b32_dpp v87, v7, v3, vcc row_ror:8 row_mask:0xf bank_mask:0xf
	v_cndmask_b32_dpp v76, v250, v246, vcc row_ror:8 row_mask:0xf bank_mask:0xf
	v_cndmask_b32_dpp v77, v251, v247, vcc row_ror:8 row_mask:0xf bank_mask:0xf
	v_cndmask_b32_dpp v78, v208, v248, vcc row_ror:8 row_mask:0xf bank_mask:0xf
	v_cndmask_b32_dpp v79, v209, v249, vcc row_ror:8 row_mask:0xf bank_mask:0xf
	s_not_b64 vcc, s[6:7]
	v_cndmask_b32_dpp v80, v0, v4, vcc row_ror:8 row_mask:0xf bank_mask:0xf
	v_cndmask_b32_dpp v81, v1, v5, vcc row_ror:8 row_mask:0xf bank_mask:0xf
	v_cndmask_b32_dpp v82, v2, v6, vcc row_ror:8 row_mask:0xf bank_mask:0xf
	v_cndmask_b32_dpp v83, v3, v7, vcc row_ror:8 row_mask:0xf bank_mask:0xf
	v_cndmask_b32_dpp v72, v246, v250, vcc row_ror:8 row_mask:0xf bank_mask:0xf
	v_cndmask_b32_dpp v73, v247, v251, vcc row_ror:8 row_mask:0xf bank_mask:0xf
	v_cndmask_b32_dpp v74, v248, v208, vcc row_ror:8 row_mask:0xf bank_mask:0xf
	v_cndmask_b32_dpp v75, v249, v209, vcc row_ror:8 row_mask:0xf bank_mask:0xf
	global_store_dwordx4 v171, v[84:87], s[2:3]
	global_store_dwordx4 v171, v[80:83], s[18:19]
	global_store_dwordx4 v171, v[76:79], s[78:79]
	global_store_dwordx4 v171, v[72:75], s[22:23]
	s_waitcnt vmcnt(6)
	v_pk_fma_f32 v[68:69], v[68:69], v[142:143], v[238:239]
	v_pk_fma_f32 v[70:71], v[70:71], v[144:145], v[240:241]
	v_pk_fma_f32 v[64:65], v[64:65], v[150:151], v[242:243]
	v_pk_fma_f32 v[66:67], v[66:67], v[152:153], v[244:245]
	v_pk_fma_f32 v[60:61], v[60:61], v[138:139], v[196:197]
	v_pk_fma_f32 v[62:63], v[62:63], v[140:141], v[198:199]
	v_pk_fma_f32 v[56:57], v[56:57], v[146:147], v[200:201]
	v_pk_fma_f32 v[58:59], v[58:59], v[148:149], v[202:203]
	global_load_dwordx4 v[238:241], v96, s[14:15] offset:128
	global_load_dwordx4 v[242:245], v96, s[14:15] offset:144
	s_add_u32 s14, s14, 0x10000
	s_addc_u32 s15, s15, 0
	global_load_dwordx4 v[196:199], v96, s[14:15]
	global_load_dwordx4 v[200:203], v96, s[14:15] offset:16
	v_cvt_pk_bf16_f32 v0, v68, v69
	v_cvt_pk_bf16_f32 v1, v70, v71
	v_cvt_pk_bf16_f32 v2, v64, v65
	v_cvt_pk_bf16_f32 v3, v66, v67
	v_cvt_pk_bf16_f32 v4, v60, v61
	v_cvt_pk_bf16_f32 v5, v62, v63
	v_cvt_pk_bf16_f32 v6, v56, v57
	v_cvt_pk_bf16_f32 v7, v58, v59
	v_mul_f32_e32 v246, v69, v69
	v_mul_f32_e32 v248, v71, v71
	v_fmac_f32_e32 v246, v68, v68
	v_fmac_f32_e32 v248, v70, v70
	v_add_f32_e32 v246, v246, v248
	v_mul_f32_e32 v248, v65, v65
	v_fmac_f32_e32 v248, v64, v64
	v_add_f32_e32 v246, v246, v248
	v_mul_f32_e32 v248, v67, v67
	v_fmac_f32_e32 v248, v66, v66
	v_add_f32_e32 v246, v248, v246
	v_mul_f32_e32 v247, v61, v61
	v_mul_f32_e32 v248, v63, v63
	v_fmac_f32_e32 v247, v60, v60
	v_fmac_f32_e32 v248, v62, v62
	v_add_f32_e32 v247, v247, v248
	v_mul_f32_e32 v248, v57, v57
	v_fmac_f32_e32 v248, v56, v56
	v_add_f32_e32 v247, v247, v248
	v_mul_f32_e32 v248, v59, v59
	v_fmac_f32_e32 v248, v58, v58
	v_add_f32_e32 v247, v248, v247
	v_add_f32_e32 v246, v246, v247
	v_mov_b32_e32 v247, v246
	s_nop 1
	v_permlane16_swap_b32_e32 v246, v247
	s_nop 1
	v_add_f32_e32 v246, v246, v247
	v_mov_b32_e32 v247, v246
	s_nop 1
	v_permlane32_swap_b32_e32 v246, v247
	v_add_u32_e32 v248, s8, v223
	s_nop 0
	v_add_f32_e32 v246, v246, v247
	s_mov_b64 exec, s[44:45]
	ds_write_b32 v248, v246 offset:2048
	s_mov_b64 exec, -1
	v_pk_mul_f32 v[68:69], v[180:181], v[68:69]
	v_pk_mul_f32 v[70:71], v[182:183], v[70:71]
	v_pk_mul_f32 v[64:65], v[184:185], v[64:65]
	v_pk_mul_f32 v[66:67], v[186:187], v[66:67]
	v_pk_mul_f32 v[60:61], v[188:189], v[60:61]
	v_pk_mul_f32 v[62:63], v[190:191], v[62:63]
	v_pk_mul_f32 v[56:57], v[192:193], v[56:57]
	v_pk_mul_f32 v[58:59], v[194:195], v[58:59]
	v_cvt_pk_bf16_f32 v246, v68, v69
	v_cvt_pk_bf16_f32 v247, v70, v71
	v_cvt_pk_bf16_f32 v248, v64, v65
	v_cvt_pk_bf16_f32 v249, v66, v67
	v_cvt_pk_bf16_f32 v250, v60, v61
	v_cvt_pk_bf16_f32 v251, v62, v63
	v_cvt_pk_bf16_f32 v208, v56, v57
	v_cvt_pk_bf16_f32 v209, v58, v59
	s_add_u32 s2, s2, 0x28000
	s_addc_u32 s3, s3, 0
	s_add_u32 s18, s18, 0x28000
	s_addc_u32 s19, s19, 0
	s_add_u32 s78, s78, 0x28000
	s_addc_u32 s79, s79, 0
	s_add_u32 s22, s22, 0x28000
	s_addc_u32 s23, s23, 0
	s_mov_b64 vcc, s[6:7]
	v_cndmask_b32_dpp v68, v4, v0, vcc row_ror:8 row_mask:0xf bank_mask:0xf
	v_cndmask_b32_dpp v69, v5, v1, vcc row_ror:8 row_mask:0xf bank_mask:0xf
	v_cndmask_b32_dpp v70, v6, v2, vcc row_ror:8 row_mask:0xf bank_mask:0xf
	v_cndmask_b32_dpp v71, v7, v3, vcc row_ror:8 row_mask:0xf bank_mask:0xf
	v_cndmask_b32_dpp v60, v250, v246, vcc row_ror:8 row_mask:0xf bank_mask:0xf
	v_cndmask_b32_dpp v61, v251, v247, vcc row_ror:8 row_mask:0xf bank_mask:0xf
	v_cndmask_b32_dpp v62, v208, v248, vcc row_ror:8 row_mask:0xf bank_mask:0xf
	v_cndmask_b32_dpp v63, v209, v249, vcc row_ror:8 row_mask:0xf bank_mask:0xf
	s_not_b64 vcc, s[6:7]
	v_cndmask_b32_dpp v64, v0, v4, vcc row_ror:8 row_mask:0xf bank_mask:0xf
	v_cndmask_b32_dpp v65, v1, v5, vcc row_ror:8 row_mask:0xf bank_mask:0xf
	v_cndmask_b32_dpp v66, v2, v6, vcc row_ror:8 row_mask:0xf bank_mask:0xf
	v_cndmask_b32_dpp v67, v3, v7, vcc row_ror:8 row_mask:0xf bank_mask:0xf
	v_cndmask_b32_dpp v56, v246, v250, vcc row_ror:8 row_mask:0xf bank_mask:0xf
	v_cndmask_b32_dpp v57, v247, v251, vcc row_ror:8 row_mask:0xf bank_mask:0xf
	v_cndmask_b32_dpp v58, v248, v208, vcc row_ror:8 row_mask:0xf bank_mask:0xf
	v_cndmask_b32_dpp v59, v249, v209, vcc row_ror:8 row_mask:0xf bank_mask:0xf
	global_store_dwordx4 v171, v[68:71], s[2:3]
	global_store_dwordx4 v171, v[64:67], s[18:19]
	global_store_dwordx4 v171, v[60:63], s[78:79]
	global_store_dwordx4 v171, v[56:59], s[22:23]
	s_waitcnt vmcnt(6)
	v_pk_fma_f32 v[52:53], v[52:53], v[142:143], v[204:205]
	v_pk_fma_f32 v[54:55], v[54:55], v[144:145], v[206:207]
	v_pk_fma_f32 v[48:49], v[48:49], v[150:151], v[234:235]
	v_pk_fma_f32 v[50:51], v[50:51], v[152:153], v[236:237]
	v_pk_fma_f32 v[44:45], v[44:45], v[138:139], v[238:239]
	v_pk_fma_f32 v[46:47], v[46:47], v[140:141], v[240:241]
	v_pk_fma_f32 v[40:41], v[40:41], v[146:147], v[242:243]
	v_pk_fma_f32 v[42:43], v[42:43], v[148:149], v[244:245]
	global_load_dwordx4 v[204:207], v96, s[14:15] offset:128
	global_load_dwordx4 v[234:237], v96, s[14:15] offset:144
	s_add_u32 s14, s14, 0x10000
	s_addc_u32 s15, s15, 0
	global_load_dwordx4 v[238:241], v96, s[14:15]
	global_load_dwordx4 v[242:245], v96, s[14:15] offset:16
	v_cvt_pk_bf16_f32 v0, v52, v53
	v_cvt_pk_bf16_f32 v1, v54, v55
	v_cvt_pk_bf16_f32 v2, v48, v49
	v_cvt_pk_bf16_f32 v3, v50, v51
	v_cvt_pk_bf16_f32 v4, v44, v45
	v_cvt_pk_bf16_f32 v5, v46, v47
	v_cvt_pk_bf16_f32 v6, v40, v41
	v_cvt_pk_bf16_f32 v7, v42, v43
	v_mul_f32_e32 v246, v53, v53
	v_mul_f32_e32 v248, v55, v55
	v_fmac_f32_e32 v246, v52, v52
	v_fmac_f32_e32 v248, v54, v54
	v_add_f32_e32 v246, v246, v248
	v_mul_f32_e32 v248, v49, v49
	v_fmac_f32_e32 v248, v48, v48
	v_add_f32_e32 v246, v246, v248
	v_mul_f32_e32 v248, v51, v51
	v_fmac_f32_e32 v248, v50, v50
	v_add_f32_e32 v246, v248, v246
	v_mul_f32_e32 v247, v45, v45
	v_mul_f32_e32 v248, v47, v47
	v_fmac_f32_e32 v247, v44, v44
	v_fmac_f32_e32 v248, v46, v46
	v_add_f32_e32 v247, v247, v248
	v_mul_f32_e32 v248, v41, v41
	v_fmac_f32_e32 v248, v40, v40
	v_add_f32_e32 v247, v247, v248
	v_mul_f32_e32 v248, v43, v43
	v_fmac_f32_e32 v248, v42, v42
	v_add_f32_e32 v247, v248, v247
	v_add_f32_e32 v246, v246, v247
	v_mov_b32_e32 v247, v246
	s_nop 1
	v_permlane16_swap_b32_e32 v246, v247
	s_nop 1
	v_add_f32_e32 v246, v246, v247
	v_mov_b32_e32 v247, v246
	s_nop 1
	v_permlane32_swap_b32_e32 v246, v247
	v_add_u32_e32 v248, s8, v223
	s_nop 0
	v_add_f32_e32 v246, v246, v247
	s_mov_b64 exec, s[44:45]
	ds_write_b32 v248, v246 offset:2304
	s_mov_b64 exec, -1
	v_pk_mul_f32 v[52:53], v[180:181], v[52:53]
	v_pk_mul_f32 v[54:55], v[182:183], v[54:55]
	v_pk_mul_f32 v[48:49], v[184:185], v[48:49]
	v_pk_mul_f32 v[50:51], v[186:187], v[50:51]
	v_pk_mul_f32 v[44:45], v[188:189], v[44:45]
	v_pk_mul_f32 v[46:47], v[190:191], v[46:47]
	v_pk_mul_f32 v[40:41], v[192:193], v[40:41]
	v_pk_mul_f32 v[42:43], v[194:195], v[42:43]
	v_cvt_pk_bf16_f32 v246, v52, v53
	v_cvt_pk_bf16_f32 v247, v54, v55
	v_cvt_pk_bf16_f32 v248, v48, v49
	v_cvt_pk_bf16_f32 v249, v50, v51
	v_cvt_pk_bf16_f32 v250, v44, v45
	v_cvt_pk_bf16_f32 v251, v46, v47
	v_cvt_pk_bf16_f32 v208, v40, v41
	v_cvt_pk_bf16_f32 v209, v42, v43
	s_add_u32 s2, s2, 0x8000
	s_addc_u32 s3, s3, 0
	s_add_u32 s18, s18, 0x8000
	s_addc_u32 s19, s19, 0
	s_add_u32 s78, s78, 0x8000
	s_addc_u32 s79, s79, 0
	s_add_u32 s22, s22, 0x8000
	s_addc_u32 s23, s23, 0
	s_mov_b64 vcc, s[6:7]
	v_cndmask_b32_dpp v52, v4, v0, vcc row_ror:8 row_mask:0xf bank_mask:0xf
	v_cndmask_b32_dpp v53, v5, v1, vcc row_ror:8 row_mask:0xf bank_mask:0xf
	v_cndmask_b32_dpp v54, v6, v2, vcc row_ror:8 row_mask:0xf bank_mask:0xf
	v_cndmask_b32_dpp v55, v7, v3, vcc row_ror:8 row_mask:0xf bank_mask:0xf
	v_cndmask_b32_dpp v44, v250, v246, vcc row_ror:8 row_mask:0xf bank_mask:0xf
	v_cndmask_b32_dpp v45, v251, v247, vcc row_ror:8 row_mask:0xf bank_mask:0xf
	v_cndmask_b32_dpp v46, v208, v248, vcc row_ror:8 row_mask:0xf bank_mask:0xf
	v_cndmask_b32_dpp v47, v209, v249, vcc row_ror:8 row_mask:0xf bank_mask:0xf
	s_not_b64 vcc, s[6:7]
	v_cndmask_b32_dpp v48, v0, v4, vcc row_ror:8 row_mask:0xf bank_mask:0xf
	v_cndmask_b32_dpp v49, v1, v5, vcc row_ror:8 row_mask:0xf bank_mask:0xf
	v_cndmask_b32_dpp v50, v2, v6, vcc row_ror:8 row_mask:0xf bank_mask:0xf
	v_cndmask_b32_dpp v51, v3, v7, vcc row_ror:8 row_mask:0xf bank_mask:0xf
	v_cndmask_b32_dpp v40, v246, v250, vcc row_ror:8 row_mask:0xf bank_mask:0xf
	v_cndmask_b32_dpp v41, v247, v251, vcc row_ror:8 row_mask:0xf bank_mask:0xf
	v_cndmask_b32_dpp v42, v248, v208, vcc row_ror:8 row_mask:0xf bank_mask:0xf
	v_cndmask_b32_dpp v43, v249, v209, vcc row_ror:8 row_mask:0xf bank_mask:0xf
	global_store_dwordx4 v171, v[52:55], s[2:3]
	global_store_dwordx4 v171, v[48:51], s[18:19]
	global_store_dwordx4 v171, v[44:47], s[78:79]
	global_store_dwordx4 v171, v[40:43], s[22:23]
	s_waitcnt vmcnt(6)
	v_pk_fma_f32 v[36:37], v[36:37], v[142:143], v[196:197]
	v_pk_fma_f32 v[38:39], v[38:39], v[144:145], v[198:199]
	v_pk_fma_f32 v[32:33], v[32:33], v[150:151], v[200:201]
	v_pk_fma_f32 v[34:35], v[34:35], v[152:153], v[202:203]
	v_pk_fma_f32 v[28:29], v[28:29], v[138:139], v[204:205]
	v_pk_fma_f32 v[30:31], v[30:31], v[140:141], v[206:207]
	v_pk_fma_f32 v[24:25], v[24:25], v[146:147], v[234:235]
	v_pk_fma_f32 v[26:27], v[26:27], v[148:149], v[236:237]
	global_load_dwordx4 v[196:199], v96, s[14:15] offset:128
	global_load_dwordx4 v[200:203], v96, s[14:15] offset:144
	v_cvt_pk_bf16_f32 v0, v36, v37
	v_cvt_pk_bf16_f32 v1, v38, v39
	v_cvt_pk_bf16_f32 v2, v32, v33
	v_cvt_pk_bf16_f32 v3, v34, v35
	v_cvt_pk_bf16_f32 v4, v28, v29
	v_cvt_pk_bf16_f32 v5, v30, v31
	v_cvt_pk_bf16_f32 v6, v24, v25
	v_cvt_pk_bf16_f32 v7, v26, v27
	v_mul_f32_e32 v246, v37, v37
	v_mul_f32_e32 v248, v39, v39
	v_fmac_f32_e32 v246, v36, v36
	v_fmac_f32_e32 v248, v38, v38
	v_add_f32_e32 v246, v246, v248
	v_mul_f32_e32 v248, v33, v33
	v_fmac_f32_e32 v248, v32, v32
	v_add_f32_e32 v246, v246, v248
	v_mul_f32_e32 v248, v35, v35
	v_fmac_f32_e32 v248, v34, v34
	v_add_f32_e32 v246, v248, v246
	v_mul_f32_e32 v247, v29, v29
	v_mul_f32_e32 v248, v31, v31
	v_fmac_f32_e32 v247, v28, v28
	v_fmac_f32_e32 v248, v30, v30
	v_add_f32_e32 v247, v247, v248
	v_mul_f32_e32 v248, v25, v25
	v_fmac_f32_e32 v248, v24, v24
	v_add_f32_e32 v247, v247, v248
	v_mul_f32_e32 v248, v27, v27
	v_fmac_f32_e32 v248, v26, v26
	v_add_f32_e32 v247, v248, v247
	v_add_f32_e32 v246, v246, v247
	v_mov_b32_e32 v247, v246
	s_nop 1
	v_permlane16_swap_b32_e32 v246, v247
	s_nop 1
	v_add_f32_e32 v246, v246, v247
	v_mov_b32_e32 v247, v246
	s_nop 1
	v_permlane32_swap_b32_e32 v246, v247
	v_add_u32_e32 v248, s8, v223
	s_nop 0
	v_add_f32_e32 v246, v246, v247
	s_mov_b64 exec, s[44:45]
	ds_write_b32 v248, v246 offset:2560
	s_mov_b64 exec, -1
	v_pk_mul_f32 v[36:37], v[180:181], v[36:37]
	v_pk_mul_f32 v[38:39], v[182:183], v[38:39]
	v_pk_mul_f32 v[32:33], v[184:185], v[32:33]
	v_pk_mul_f32 v[34:35], v[186:187], v[34:35]
	v_pk_mul_f32 v[28:29], v[188:189], v[28:29]
	v_pk_mul_f32 v[30:31], v[190:191], v[30:31]
	v_pk_mul_f32 v[24:25], v[192:193], v[24:25]
	v_pk_mul_f32 v[26:27], v[194:195], v[26:27]
	v_cvt_pk_bf16_f32 v246, v36, v37
	v_cvt_pk_bf16_f32 v247, v38, v39
	v_cvt_pk_bf16_f32 v248, v32, v33
	v_cvt_pk_bf16_f32 v249, v34, v35
	v_cvt_pk_bf16_f32 v250, v28, v29
	v_cvt_pk_bf16_f32 v251, v30, v31
	v_cvt_pk_bf16_f32 v208, v24, v25
	v_cvt_pk_bf16_f32 v209, v26, v27
	s_add_u32 s2, s2, 0x8000
	s_addc_u32 s3, s3, 0
	s_add_u32 s18, s18, 0x8000
	s_addc_u32 s19, s19, 0
	s_add_u32 s78, s78, 0x8000
	s_addc_u32 s79, s79, 0
	s_add_u32 s22, s22, 0x8000
	s_addc_u32 s23, s23, 0
	s_mov_b64 vcc, s[6:7]
	v_cndmask_b32_dpp v36, v4, v0, vcc row_ror:8 row_mask:0xf bank_mask:0xf
	v_cndmask_b32_dpp v37, v5, v1, vcc row_ror:8 row_mask:0xf bank_mask:0xf
	v_cndmask_b32_dpp v38, v6, v2, vcc row_ror:8 row_mask:0xf bank_mask:0xf
	v_cndmask_b32_dpp v39, v7, v3, vcc row_ror:8 row_mask:0xf bank_mask:0xf
	v_cndmask_b32_dpp v28, v250, v246, vcc row_ror:8 row_mask:0xf bank_mask:0xf
	v_cndmask_b32_dpp v29, v251, v247, vcc row_ror:8 row_mask:0xf bank_mask:0xf
	v_cndmask_b32_dpp v30, v208, v248, vcc row_ror:8 row_mask:0xf bank_mask:0xf
	v_cndmask_b32_dpp v31, v209, v249, vcc row_ror:8 row_mask:0xf bank_mask:0xf
	s_not_b64 vcc, s[6:7]
	v_cndmask_b32_dpp v32, v0, v4, vcc row_ror:8 row_mask:0xf bank_mask:0xf
	v_cndmask_b32_dpp v33, v1, v5, vcc row_ror:8 row_mask:0xf bank_mask:0xf
	v_cndmask_b32_dpp v34, v2, v6, vcc row_ror:8 row_mask:0xf bank_mask:0xf
	v_cndmask_b32_dpp v35, v3, v7, vcc row_ror:8 row_mask:0xf bank_mask:0xf
	v_cndmask_b32_dpp v24, v246, v250, vcc row_ror:8 row_mask:0xf bank_mask:0xf
	v_cndmask_b32_dpp v25, v247, v251, vcc row_ror:8 row_mask:0xf bank_mask:0xf
	v_cndmask_b32_dpp v26, v248, v208, vcc row_ror:8 row_mask:0xf bank_mask:0xf
	v_cndmask_b32_dpp v27, v249, v209, vcc row_ror:8 row_mask:0xf bank_mask:0xf
	global_store_dwordx4 v171, v[36:39], s[2:3]
	global_store_dwordx4 v171, v[32:35], s[18:19]
	global_store_dwordx4 v171, v[28:31], s[78:79]
	global_store_dwordx4 v171, v[24:27], s[22:23]
	s_waitcnt vmcnt(4)
	v_pk_fma_f32 v[20:21], v[20:21], v[142:143], v[238:239]
	v_pk_fma_f32 v[22:23], v[22:23], v[144:145], v[240:241]
	v_pk_fma_f32 v[16:17], v[16:17], v[150:151], v[242:243]
	v_pk_fma_f32 v[18:19], v[18:19], v[152:153], v[244:245]
	v_pk_fma_f32 v[12:13], v[12:13], v[138:139], v[196:197]
	v_pk_fma_f32 v[14:15], v[14:15], v[140:141], v[198:199]
	v_pk_fma_f32 v[8:9], v[8:9], v[146:147], v[200:201]
	v_pk_fma_f32 v[10:11], v[10:11], v[148:149], v[202:203]
	v_cvt_pk_bf16_f32 v0, v20, v21
	v_cvt_pk_bf16_f32 v1, v22, v23
	v_cvt_pk_bf16_f32 v2, v16, v17
	v_cvt_pk_bf16_f32 v3, v18, v19
	v_cvt_pk_bf16_f32 v4, v12, v13
	v_cvt_pk_bf16_f32 v5, v14, v15
	v_cvt_pk_bf16_f32 v6, v8, v9
	v_cvt_pk_bf16_f32 v7, v10, v11
	v_mul_f32_e32 v246, v21, v21
	v_mul_f32_e32 v248, v23, v23
	v_fmac_f32_e32 v246, v20, v20
	v_fmac_f32_e32 v248, v22, v22
	v_add_f32_e32 v246, v246, v248
	v_mul_f32_e32 v248, v17, v17
	v_fmac_f32_e32 v248, v16, v16
	v_add_f32_e32 v246, v246, v248
	v_mul_f32_e32 v248, v19, v19
	v_fmac_f32_e32 v248, v18, v18
	v_add_f32_e32 v246, v248, v246
	v_mul_f32_e32 v247, v13, v13
	v_mul_f32_e32 v248, v15, v15
	v_fmac_f32_e32 v247, v12, v12
	v_fmac_f32_e32 v248, v14, v14
	v_add_f32_e32 v247, v247, v248
	v_mul_f32_e32 v248, v9, v9
	v_fmac_f32_e32 v248, v8, v8
	v_add_f32_e32 v247, v247, v248
	v_mul_f32_e32 v248, v11, v11
	v_fmac_f32_e32 v248, v10, v10
	v_add_f32_e32 v247, v248, v247
	v_add_f32_e32 v246, v246, v247
	v_mov_b32_e32 v247, v246
	s_nop 1
	v_permlane16_swap_b32_e32 v246, v247
	s_nop 1
	v_add_f32_e32 v246, v246, v247
	v_mov_b32_e32 v247, v246
	s_nop 1
	v_permlane32_swap_b32_e32 v246, v247
	v_add_u32_e32 v248, s8, v223
	s_nop 0
	v_add_f32_e32 v246, v246, v247
	s_mov_b64 exec, s[44:45]
	ds_write_b32 v248, v246 offset:2816
	s_mov_b64 exec, -1
	v_pk_mul_f32 v[20:21], v[180:181], v[20:21]
	v_pk_mul_f32 v[22:23], v[182:183], v[22:23]
	v_pk_mul_f32 v[16:17], v[184:185], v[16:17]
	v_pk_mul_f32 v[18:19], v[186:187], v[18:19]
	v_pk_mul_f32 v[12:13], v[188:189], v[12:13]
	v_pk_mul_f32 v[14:15], v[190:191], v[14:15]
	v_pk_mul_f32 v[8:9], v[192:193], v[8:9]
	v_pk_mul_f32 v[10:11], v[194:195], v[10:11]
	v_cvt_pk_bf16_f32 v246, v20, v21
	v_cvt_pk_bf16_f32 v247, v22, v23
	v_cvt_pk_bf16_f32 v248, v16, v17
	v_cvt_pk_bf16_f32 v249, v18, v19
	v_cvt_pk_bf16_f32 v250, v12, v13
	v_cvt_pk_bf16_f32 v251, v14, v15
	v_cvt_pk_bf16_f32 v208, v8, v9
	v_cvt_pk_bf16_f32 v209, v10, v11
	s_add_u32 s2, s2, 0x8000
	s_addc_u32 s3, s3, 0
	s_add_u32 s18, s18, 0x8000
	s_addc_u32 s19, s19, 0
	s_add_u32 s78, s78, 0x8000
	s_addc_u32 s79, s79, 0
	s_add_u32 s22, s22, 0x8000
	s_addc_u32 s23, s23, 0
	s_mov_b64 vcc, s[6:7]
	v_cndmask_b32_dpp v20, v4, v0, vcc row_ror:8 row_mask:0xf bank_mask:0xf
	v_cndmask_b32_dpp v21, v5, v1, vcc row_ror:8 row_mask:0xf bank_mask:0xf
	v_cndmask_b32_dpp v22, v6, v2, vcc row_ror:8 row_mask:0xf bank_mask:0xf
	v_cndmask_b32_dpp v23, v7, v3, vcc row_ror:8 row_mask:0xf bank_mask:0xf
	v_cndmask_b32_dpp v12, v250, v246, vcc row_ror:8 row_mask:0xf bank_mask:0xf
	v_cndmask_b32_dpp v13, v251, v247, vcc row_ror:8 row_mask:0xf bank_mask:0xf
	v_cndmask_b32_dpp v14, v208, v248, vcc row_ror:8 row_mask:0xf bank_mask:0xf
	v_cndmask_b32_dpp v15, v209, v249, vcc row_ror:8 row_mask:0xf bank_mask:0xf
	s_not_b64 vcc, s[6:7]
	v_cndmask_b32_dpp v16, v0, v4, vcc row_ror:8 row_mask:0xf bank_mask:0xf
	v_cndmask_b32_dpp v17, v1, v5, vcc row_ror:8 row_mask:0xf bank_mask:0xf
	v_cndmask_b32_dpp v18, v2, v6, vcc row_ror:8 row_mask:0xf bank_mask:0xf
	v_cndmask_b32_dpp v19, v3, v7, vcc row_ror:8 row_mask:0xf bank_mask:0xf
	v_cndmask_b32_dpp v8, v246, v250, vcc row_ror:8 row_mask:0xf bank_mask:0xf
	v_cndmask_b32_dpp v9, v247, v251, vcc row_ror:8 row_mask:0xf bank_mask:0xf
	v_cndmask_b32_dpp v10, v248, v208, vcc row_ror:8 row_mask:0xf bank_mask:0xf
	v_cndmask_b32_dpp v11, v249, v209, vcc row_ror:8 row_mask:0xf bank_mask:0xf
	global_store_dwordx4 v171, v[20:23], s[2:3]
	global_store_dwordx4 v171, v[16:19], s[18:19]
	global_store_dwordx4 v171, v[12:15], s[78:79]
	global_store_dwordx4 v171, v[8:11], s[22:23]
	s_mov_b32 s100, 1
	s_branch .LBB0_714
